# scan state image written as paired b32 (DPP lane exchange) instead of b16 LDS writes
# baseline (speedup 1.0000x reference)
; #define LAS __attribute__((address_space(3)))
; #define MFMA32(a, b, c) __builtin_amdgcn_mfma_f32_32x32x16_bf16((a), (b), (c), 0, 0, 0)
; template <bool XW, int PASS, bool RMW> ...
;     ...
; #pragma unroll
;       for (int i = 0; i < 16; ++i) { st0[i] *= cd; st1[i] *= cd; }
; #pragma unroll
;       for (int sb = 0; sb < 2; ++sb) {
;         bf16x8 a0[4], a1[4];
; #pragma unroll
;         for (int k = 0; k < 4; ++k) { a0[k] = *(const LAS bf16x8*)(vimg + (cc & 1) * 16384 + (4 * sb + k) * 1024 + lane * 16); a1[k] = *(const LAS bf16x8*)(vimg + (cc & 1) * 16384 + 8192 + (4 * sb + k) * 1024 + lane * 16); }
; #pragma unroll
;         for (int k = 0; k < 4; ++k) { st0 = MFMA32(a0[k], kb0[4 * sb + k], st0); st1 = MFMA32(a1[k], kb0[4 * sb + k], st1); }
;         asm volatile("" : "+v"(st0), "+v"(st1) :: "memory");
; #pragma unroll
;         for (int k = 0; k < 4; ++k) kb0[4 * sb + k] = ldg16(kT, kboff0 + (unsigned)cn * 262144u + 1024u * (4 * sb + k));
;       }
; #pragma unroll
;       for (int t = 0; t < 2; ++t) {
;         const int sv = 2 * dq + t;
;         *(LAS bf16x8*)(vimg + ((cc + 1) & 1) * 16384 + et * 8192 + sv * 1024 + lane * 16) = scale_tab(vr[t], kdec + 16 * sv + 8 * h);
;         vr[t] = ldg16(vT, vaoff0 + (unsigned)cnn * 524288u + 1024u * sv);
;       }
.LBB0_79:
	s_and_b32 s37, s0, 0x4000
	s_waitcnt vmcnt(0)
	v_lshlrev_b32_e32 v88, 16, v68
	v_and_b32_e32 v89, 0xffff0000, v68
	v_add_u32_e32 v68, s37, v218
	v_lshlrev_b32_e32 v80, 16, v64
	v_and_b32_e32 v81, 0xffff0000, v64
	v_lshlrev_b32_e32 v82, 16, v65
	v_and_b32_e32 v83, 0xffff0000, v65
	v_lshlrev_b32_e32 v84, 16, v66
	v_and_b32_e32 v85, 0xffff0000, v66
	v_lshlrev_b32_e32 v86, 16, v67
	v_and_b32_e32 v87, 0xffff0000, v67
	ds_read_b128 v[160:163], v68
	ds_read_b128 v[228:231], v68 offset:8192
	ds_read_b128 v[232:235], v68 offset:1024
	ds_read_b128 v[236:239], v68 offset:9216
	ds_read_b128 v[240:243], v68 offset:2048
	ds_read_b128 v[244:247], v68 offset:10240
	ds_read_b128 v[248:251], v68 offset:3072
	v_mov_b32_e32 v73, v72
	v_pk_mul_f32 v[0:1], v[74:75], v[0:1]
	v_pk_mul_f32 v[14:15], v[72:73], v[14:15]
	v_pk_mul_f32 v[12:13], v[72:73], v[12:13]
	v_pk_mul_f32 v[10:11], v[72:73], v[10:11]
	v_pk_mul_f32 v[8:9], v[72:73], v[8:9]
	v_pk_mul_f32 v[6:7], v[72:73], v[6:7]
	v_pk_mul_f32 v[4:5], v[72:73], v[4:5]
	v_pk_mul_f32 v[2:3], v[72:73], v[2:3]
	v_pk_mul_f32 v[16:17], v[74:75], v[16:17]
	v_pk_mul_f32 v[30:31], v[72:73], v[30:31]
	s_waitcnt lgkmcnt(6)
	v_mfma_f32_32x32x16_bf16 v[0:15], v[160:163], v[60:63], v[0:15]
	ds_read_b128 v[160:163], v68 offset:11264
	v_mul_f32_e64 v28, v72, v28
	v_mul_f32_e64 v29, v73, v29
	v_mul_f32_e64 v26, v72, v26
	v_mul_f32_e64 v27, v73, v27
	v_pk_mul_f32 v[24:25], v[72:73], v[24:25]
	v_pk_mul_f32 v[22:23], v[72:73], v[22:23]
	v_pk_mul_f32 v[20:21], v[72:73], v[20:21]
	v_pk_mul_f32 v[18:19], v[72:73], v[18:19]
	s_add_i32 s2, s36, 1
	s_add_i32 s36, s36, 2
	s_waitcnt lgkmcnt(6)
	v_mfma_f32_32x32x16_bf16 v[16:31], v[228:231], v[60:63], v[16:31]
	ds_read_b128 v[228:231], v68 offset:4096
	s_min_u32 s37, s2, s5
	s_min_u32 s36, s36, s5
	v_lshlrev_b32_e32 v90, 16, v69
	v_and_b32_e32 v91, 0xffff0000, v69
	v_lshlrev_b32_e32 v92, 16, v70
	v_and_b32_e32 v93, 0xffff0000, v70
	s_waitcnt lgkmcnt(6)
	v_mfma_f32_32x32x16_bf16 v[0:15], v[232:235], v[56:59], v[0:15]
	ds_read_b128 v[232:235], v68 offset:12288
	v_lshlrev_b32_e32 v94, 16, v71
	v_and_b32_e32 v95, 0xffff0000, v71
	s_addk_i32 s0, 0x4000
	s_and_b32 s38, s0, 0x4000
	v_add_u32_e32 v73, s38, v198
	v_add_u32_e32 v97, s3, v73
	s_waitcnt lgkmcnt(6)
	v_mfma_f32_32x32x16_bf16 v[16:31], v[236:239], v[56:59], v[16:31]
	ds_read_b128 v[236:239], v68 offset:5120
	s_xor_b32 s1, s1, 1
	v_add_u32_e32 v73, s33, v73
	s_cmp_lg_u32 s4, s2
	s_waitcnt lgkmcnt(6)
	v_mfma_f32_32x32x16_bf16 v[0:15], v[240:243], v[52:55], v[0:15]
	ds_read_b128 v[240:243], v68 offset:13312
	s_waitcnt lgkmcnt(6)
	v_mfma_f32_32x32x16_bf16 v[16:31], v[244:247], v[52:55], v[16:31]
	ds_read_b128 v[244:247], v68 offset:6144
	v_lshl_add_u32 v56, s37, 18, v223
	v_lshl_add_u32 v57, s36, 19, v224
	v_or_b32_e32 v58, 0x400, v56
	v_or_b32_e32 v64, 0x800, v56
	v_or_b32_e32 v65, 0xc00, v56
	v_or_b32_e32 v69, 0x1000, v56
	s_waitcnt lgkmcnt(6)
	v_mfma_f32_32x32x16_bf16 v[0:15], v[248:251], v[48:51], v[0:15]
	ds_read_b128 v[248:251], v68 offset:14336
	v_or_b32_e32 v70, 0x1400, v56
	v_or_b32_e32 v71, 0x1800, v56
	v_or_b32_e32 v96, 0x1c00, v56
	v_or_b32_e32 v98, s3, v57
	v_or_b32_e32 v99, s33, v57
	s_mul_i32 s36, s1, 0x8400
	s_waitcnt lgkmcnt(6)
	v_mfma_f32_32x32x16_bf16 v[16:31], v[160:163], v[48:51], v[16:31]
	ds_read_b128 v[160:163], v68 offset:7168
	s_waitcnt lgkmcnt(6)
	v_mfma_f32_32x32x16_bf16 v[0:15], v[228:231], v[44:47], v[0:15]
	ds_read_b128 v[228:231], v68 offset:15360
	s_waitcnt lgkmcnt(6)
	v_mfma_f32_32x32x16_bf16 v[16:31], v[232:235], v[44:47], v[16:31]
	s_waitcnt lgkmcnt(5)
	v_mfma_f32_32x32x16_bf16 v[0:15], v[236:239], v[40:43], v[0:15]
	s_waitcnt lgkmcnt(4)
	v_mfma_f32_32x32x16_bf16 v[16:31], v[240:243], v[40:43], v[16:31]
	s_waitcnt lgkmcnt(3)
	v_mfma_f32_32x32x16_bf16 v[0:15], v[244:247], v[36:39], v[0:15]
	s_waitcnt lgkmcnt(2)
	v_mfma_f32_32x32x16_bf16 v[16:31], v[248:251], v[36:39], v[16:31]
	s_waitcnt lgkmcnt(1)
	v_mfma_f32_32x32x16_bf16 v[0:15], v[160:163], v[32:35], v[0:15]
	global_load_dwordx4 v[60:63], v56, s[14:15]
	s_nop 0
	global_load_dwordx4 v[56:59], v58, s[14:15]
	s_nop 0
	global_load_dwordx4 v[52:55], v64, s[14:15]
	global_load_dwordx4 v[48:51], v65, s[14:15]
	s_waitcnt lgkmcnt(0)
	v_mfma_f32_32x32x16_bf16 v[16:31], v[228:231], v[32:35], v[16:31]
	ds_read_b128 v[64:67], v76
	global_load_dwordx4 v[44:47], v69, s[14:15]
	global_load_dwordx4 v[40:43], v70, s[14:15]
	global_load_dwordx4 v[36:39], v71, s[14:15]
	global_load_dwordx4 v[32:35], v96, s[14:15]
	ds_read_b128 v[68:71], v76 offset:16
	s_waitcnt lgkmcnt(1)
; #define LAS __attribute__((address_space(3)))
; DI unsigned cvt_pk_bf16(float lo, float hi) { unsigned r; asm volatile("v_cvt_pk_bf16_f32 %0, %1, %2" : "=v"(r) : "v"(lo), "v"(hi)); return r; }
; template <bool XW, int PASS, bool RMW> ...
;     ...
;       for (int t = 0; t < 2; ++t) {
;         const int sv = 2 * dq + t;
;         *(LAS bf16x8*)(vimg + ((cc + 1) & 1) * 16384 + et * 8192 + sv * 1024 + lane * 16) = scale_tab(vr[t], kdec + 16 * sv + 8 * h);
;         vr[t] = ldg16(vT, vaoff0 + (unsigned)cnn * 524288u + 1024u * sv);
;       }
;       LAS bf16_t* sw = Sb + (pbuf ^ 1) * SBE + (4 * h) * 264 + 32 * w + r;
; #pragma unroll
;       for (int i = 0; i < 16; ++i) {
;         const int eo = ((i & 3) + 8 * (i >> 2)) * 264;
;         const unsigned pkw = cvt_pk_bf16(st0[i], st1[i]);
;         sw[eo] = (bf16_t)(pkw & 0xffffu);
;         sw[eo + 32 * 264] = (bf16_t)(pkw >> 16);
;       }
;       lds_barrier();
;       pbuf ^= 1;
	v_mul_f32_e32 v64, v64, v80
	v_mul_f32_e32 v65, v65, v81
	s_waitcnt lgkmcnt(0)
	v_mul_f32_e32 v71, v71, v87
	v_mul_f32_e32 v66, v66, v82
	v_mul_f32_e32 v67, v67, v83
	v_mul_f32_e32 v80, v68, v84
	v_mul_f32_e32 v81, v69, v85
	v_mul_f32_e32 v82, v70, v86
	v_cvt_pk_bf16_f32 v68, v64, v65
	v_cvt_pk_bf16_f32 v69, v66, v67
	v_cvt_pk_bf16_f32 v70, v80, v81
	v_cvt_pk_bf16_f32 v71, v82, v71
	ds_write_b128 v97, v[68:71]
	global_load_dwordx4 v[64:67], v98, s[16:17]
	ds_read_b128 v[68:71], v77
	ds_read_b128 v[80:83], v77 offset:16
	s_waitcnt lgkmcnt(1)
	v_mul_f32_e32 v68, v68, v88
	v_mul_f32_e32 v69, v69, v89
	v_mul_f32_e32 v70, v70, v90
	v_mul_f32_e32 v71, v71, v91
	s_waitcnt lgkmcnt(0)
	v_mul_f32_e32 v83, v83, v95
	v_mul_f32_e32 v84, v80, v92
	v_mul_f32_e32 v85, v81, v93
	v_mul_f32_e32 v86, v82, v94
	v_cvt_pk_bf16_f32 v80, v68, v69
	v_cvt_pk_bf16_f32 v81, v70, v71
	v_cvt_pk_bf16_f32 v82, v84, v85
	v_cvt_pk_bf16_f32 v83, v86, v83
	global_load_dwordx4 v[68:71], v99, s[16:17]
	v_add_u32_e32 v84, s36, v199
	ds_write_b128 v73, v[80:83]
	v_mbcnt_lo_u32_b32 v251, -1, 0
	v_mbcnt_hi_u32_b32 v251, -1, v251
	v_and_b32_e32 v251, 1, v251
	v_sub_u32_e32 v250, 0, v251
	v_and_b32_e32 v248, 0x06060606, v250
	v_xor_b32_e32 v248, 0x05040100, v248
	v_and_b32_e32 v251, 0x107e, v250
	v_add_u32_e32 v249, v84, v251
	v_cvt_pk_bf16_f32 v232, v0, v4
	v_cvt_pk_bf16_f32 v233, v1, v5
	v_cvt_pk_bf16_f32 v234, v2, v6
	v_cvt_pk_bf16_f32 v235, v3, v7
	v_cvt_pk_bf16_f32 v236, v8, v12
	v_cvt_pk_bf16_f32 v237, v9, v13
	v_cvt_pk_bf16_f32 v238, v10, v14
	v_cvt_pk_bf16_f32 v239, v11, v15
	v_mov_b32_dpp v240, v232 quad_perm:[1,0,3,2] row_mask:0xf bank_mask:0xf
	v_mov_b32_dpp v241, v233 quad_perm:[1,0,3,2] row_mask:0xf bank_mask:0xf
	v_mov_b32_dpp v242, v234 quad_perm:[1,0,3,2] row_mask:0xf bank_mask:0xf
	v_mov_b32_dpp v243, v235 quad_perm:[1,0,3,2] row_mask:0xf bank_mask:0xf
	v_mov_b32_dpp v244, v236 quad_perm:[1,0,3,2] row_mask:0xf bank_mask:0xf
	v_mov_b32_dpp v245, v237 quad_perm:[1,0,3,2] row_mask:0xf bank_mask:0xf
	v_mov_b32_dpp v246, v238 quad_perm:[1,0,3,2] row_mask:0xf bank_mask:0xf
	v_mov_b32_dpp v247, v239 quad_perm:[1,0,3,2] row_mask:0xf bank_mask:0xf
	v_perm_b32 v240, v240, v232, v248
	v_perm_b32 v241, v241, v233, v248
	v_perm_b32 v242, v242, v234, v248
	v_perm_b32 v243, v243, v235, v248
	v_perm_b32 v244, v244, v236, v248
	v_perm_b32 v245, v245, v237, v248
	v_perm_b32 v246, v246, v238, v248
	v_perm_b32 v247, v247, v239, v248
	ds_write_b32 v249, v240 offset:0
	ds_write_b32 v249, v241 offset:528
	ds_write_b32 v249, v242 offset:1056
	ds_write_b32 v249, v243 offset:1584
	ds_write_b32 v249, v244 offset:8448
	ds_write_b32 v249, v245 offset:8976
	ds_write_b32 v249, v246 offset:9504
	ds_write_b32 v249, v247 offset:10032
	v_cvt_pk_bf16_f32 v232, v16, v20
	v_cvt_pk_bf16_f32 v233, v17, v21
	v_cvt_pk_bf16_f32 v234, v18, v22
	v_cvt_pk_bf16_f32 v235, v19, v23
	v_cvt_pk_bf16_f32 v236, v24, v28
	v_cvt_pk_bf16_f32 v237, v25, v29
	v_cvt_pk_bf16_f32 v238, v26, v30
	v_cvt_pk_bf16_f32 v239, v27, v31
	v_mov_b32_dpp v240, v232 quad_perm:[1,0,3,2] row_mask:0xf bank_mask:0xf
	v_mov_b32_dpp v241, v233 quad_perm:[1,0,3,2] row_mask:0xf bank_mask:0xf
	v_mov_b32_dpp v242, v234 quad_perm:[1,0,3,2] row_mask:0xf bank_mask:0xf
	v_mov_b32_dpp v243, v235 quad_perm:[1,0,3,2] row_mask:0xf bank_mask:0xf
	v_mov_b32_dpp v244, v236 quad_perm:[1,0,3,2] row_mask:0xf bank_mask:0xf
	v_mov_b32_dpp v245, v237 quad_perm:[1,0,3,2] row_mask:0xf bank_mask:0xf
	v_mov_b32_dpp v246, v238 quad_perm:[1,0,3,2] row_mask:0xf bank_mask:0xf
	v_mov_b32_dpp v247, v239 quad_perm:[1,0,3,2] row_mask:0xf bank_mask:0xf
	v_perm_b32 v240, v240, v232, v248
	v_perm_b32 v241, v241, v233, v248
	v_perm_b32 v242, v242, v234, v248
	v_perm_b32 v243, v243, v235, v248
	v_perm_b32 v244, v244, v236, v248
	v_perm_b32 v245, v245, v237, v248
	v_perm_b32 v246, v246, v238, v248
	v_perm_b32 v247, v247, v239, v248
	ds_write_b32 v249, v240 offset:16896
	ds_write_b32 v249, v241 offset:17424
	ds_write_b32 v249, v242 offset:17952
	ds_write_b32 v249, v243 offset:18480
	ds_write_b32 v249, v244 offset:25344
	ds_write_b32 v249, v245 offset:25872
	ds_write_b32 v249, v246 offset:26400
	ds_write_b32 v249, v247 offset:26928
	s_waitcnt lgkmcnt(0)
	s_barrier
	s_mov_b32 s36, s2
	s_cbranch_scc1 .LBB0_79
	s_cmp_lg_u32 s31, 0
	s_cbranch_scc1 .LBB0_85
	s_and_saveexec_b64 s[0:1], s[6:7]
	s_cbranch_execz .LBB0_83
	v_mul_f32_e64 v0, v200, -v225
	v_exp_f32_e32 v0, v0
	ds_write_b32 v195, v0

; #define LAS __attribute__((address_space(3)))
; #define MFMA32(a, b, c) __builtin_amdgcn_mfma_f32_32x32x16_bf16((a), (b), (c), 0, 0, 0)
; template <bool XW, int PASS, bool RMW> ...
;     ...
; #pragma unroll
;       for (int i = 0; i < 16; ++i) { st0[i] *= cd; st1[i] *= cd; }
; #pragma unroll
;       for (int sb = 0; sb < 2; ++sb) {
;         bf16x8 a0[4], a1[4];
; #pragma unroll
;         for (int k = 0; k < 4; ++k) { a0[k] = *(const LAS bf16x8*)(vimg + (cc & 1) * 16384 + (4 * sb + k) * 1024 + lane * 16); a1[k] = *(const LAS bf16x8*)(vimg + (cc & 1) * 16384 + 8192 + (4 * sb + k) * 1024 + lane * 16); }
; #pragma unroll
;         for (int k = 0; k < 4; ++k) { st0 = MFMA32(a0[k], kb0[4 * sb + k], st0); st1 = MFMA32(a1[k], kb0[4 * sb + k], st1); }
;         asm volatile("" : "+v"(st0), "+v"(st1) :: "memory");
; #pragma unroll
;         for (int k = 0; k < 4; ++k) kb0[4 * sb + k] = ldg16(kT, kboff0 + (unsigned)cn * 262144u + 1024u * (4 * sb + k));
;       }
; #pragma unroll
;       for (int t = 0; t < 2; ++t) {
;         const int sv = 2 * dq + t;
;         *(LAS bf16x8*)(vimg + ((cc + 1) & 1) * 16384 + et * 8192 + sv * 1024 + lane * 16) = scale_tab(vr[t], kdec + 16 * sv + 8 * h);
;         vr[t] = ldg16(vT, vaoff0 + (unsigned)cnn * 524288u + 1024u * sv);
;       }
.LBB0_84:
	v_mov_b32_e32 v73, v72
	s_and_b32 s2, s0, 0x4000
	v_pk_mul_f32 v[14:15], v[72:73], v[14:15]
	v_pk_mul_f32 v[12:13], v[72:73], v[12:13]
	v_pk_mul_f32 v[10:11], v[72:73], v[10:11]
	v_pk_mul_f32 v[8:9], v[72:73], v[8:9]
	v_pk_mul_f32 v[6:7], v[72:73], v[6:7]
	v_pk_mul_f32 v[4:5], v[72:73], v[4:5]
	v_pk_mul_f32 v[2:3], v[72:73], v[2:3]
	v_pk_mul_f32 v[30:31], v[72:73], v[30:31]
	v_pk_mul_f32 v[28:29], v[72:73], v[28:29]
	v_pk_mul_f32 v[26:27], v[72:73], v[26:27]
	v_pk_mul_f32 v[24:25], v[72:73], v[24:25]
	v_pk_mul_f32 v[22:23], v[72:73], v[22:23]
	v_pk_mul_f32 v[20:21], v[72:73], v[20:21]
	v_pk_mul_f32 v[18:19], v[72:73], v[18:19]
	v_add_u32_e32 v73, s2, v218
	ds_read_b128 v[160:163], v73
	ds_read_b128 v[228:231], v73 offset:8192
	ds_read_b128 v[232:235], v73 offset:1024
	ds_read_b128 v[236:239], v73 offset:9216
	ds_read_b128 v[240:243], v73 offset:2048
	ds_read_b128 v[244:247], v73 offset:10240
	ds_read_b128 v[248:251], v73 offset:3072
	v_pk_mul_f32 v[0:1], v[74:75], v[0:1]
	v_pk_mul_f32 v[16:17], v[74:75], v[16:17]
	s_add_i32 s2, s36, 1
	s_waitcnt vmcnt(9)
	s_waitcnt lgkmcnt(6)
	v_mfma_f32_32x32x16_bf16 v[0:15], v[160:163], v[68:71], v[0:15]
	ds_read_b128 v[160:163], v73 offset:11264
	s_add_i32 s36, s36, 2
	s_waitcnt vmcnt(0)
	v_lshlrev_b32_e32 v90, 16, v52
	v_and_b32_e32 v91, 0xffff0000, v52
	v_lshlrev_b32_e32 v92, 16, v53
	v_and_b32_e32 v93, 0xffff0000, v53
	v_lshlrev_b32_e32 v94, 16, v54
	s_waitcnt lgkmcnt(6)
	v_mfma_f32_32x32x16_bf16 v[16:31], v[228:231], v[68:71], v[16:31]
	ds_read_b128 v[228:231], v73 offset:4096
	v_and_b32_e32 v95, 0xffff0000, v54
	v_lshlrev_b32_e32 v96, 16, v55
	v_and_b32_e32 v97, 0xffff0000, v55
	s_addk_i32 s0, 0x4000
	s_xor_b32 s1, s1, 1
	s_waitcnt lgkmcnt(6)
	v_mfma_f32_32x32x16_bf16 v[0:15], v[232:235], v[64:67], v[0:15]
	ds_read_b128 v[232:235], v73 offset:12288
	v_lshlrev_b32_e32 v82, 16, v56
	v_and_b32_e32 v83, 0xffff0000, v56
	v_lshlrev_b32_e32 v84, 16, v57
	v_and_b32_e32 v85, 0xffff0000, v57
	s_waitcnt lgkmcnt(6)
	v_mfma_f32_32x32x16_bf16 v[16:31], v[236:239], v[64:67], v[16:31]
	ds_read_b128 v[236:239], v73 offset:5120
	v_lshlrev_b32_e32 v86, 16, v58
	v_and_b32_e32 v87, 0xffff0000, v58
	v_lshlrev_b32_e32 v88, 16, v59
	v_and_b32_e32 v89, 0xffff0000, v59
	s_waitcnt lgkmcnt(6)
	v_mfma_f32_32x32x16_bf16 v[0:15], v[240:243], v[60:63], v[0:15]
	ds_read_b128 v[240:243], v73 offset:13312
	s_waitcnt lgkmcnt(6)
	v_mfma_f32_32x32x16_bf16 v[16:31], v[244:247], v[60:63], v[16:31]
	ds_read_b128 v[244:247], v73 offset:6144
	s_waitcnt lgkmcnt(6)
	v_mfma_f32_32x32x16_bf16 v[0:15], v[248:251], v[48:51], v[0:15]
	ds_read_b128 v[248:251], v73 offset:14336
	s_waitcnt lgkmcnt(6)
	v_mfma_f32_32x32x16_bf16 v[16:31], v[160:163], v[48:51], v[16:31]
	ds_read_b128 v[160:163], v73 offset:7168
	s_waitcnt lgkmcnt(6)
	v_mfma_f32_32x32x16_bf16 v[0:15], v[228:231], v[44:47], v[0:15]
	ds_read_b128 v[228:231], v73 offset:15360
	s_waitcnt lgkmcnt(6)
	v_mfma_f32_32x32x16_bf16 v[16:31], v[232:235], v[44:47], v[16:31]
	v_mov_b32_e32 v44, s2
	v_mov_b32_e32 v45, s36
	v_sub_u32_e64 v44, s5, v44 clamp
	v_sub_u32_e64 v45, s5, v45 clamp
	v_lshl_add_u32 v48, v44, 18, v223
	v_lshl_add_u32 v49, v45, 19, v224
	v_or_b32_e32 v78, s3, v49
	s_waitcnt lgkmcnt(5)
	v_mfma_f32_32x32x16_bf16 v[0:15], v[236:239], v[40:43], v[0:15]
	v_or_b32_e32 v56, 0x1800, v48
	v_or_b32_e32 v57, 0x1c00, v48
	v_or_b32_e32 v99, s33, v49
	s_and_b32 s36, s0, 0x4000
	v_add_u32_e32 v98, s36, v198
	s_mul_i32 s36, s1, 0x8400
	s_cmp_eq_u32 s4, s2
	s_waitcnt lgkmcnt(4)
	v_mfma_f32_32x32x16_bf16 v[16:31], v[240:243], v[40:43], v[16:31]
	s_waitcnt lgkmcnt(3)
	v_mfma_f32_32x32x16_bf16 v[0:15], v[244:247], v[36:39], v[0:15]
	v_add_u32_e32 v73, s3, v98
	s_waitcnt lgkmcnt(2)
	v_mfma_f32_32x32x16_bf16 v[16:31], v[248:251], v[36:39], v[16:31]
	v_or_b32_e32 v36, 0x400, v48
	v_or_b32_e32 v37, 0x800, v48
	v_or_b32_e32 v38, 0xc00, v48
	v_or_b32_e32 v39, 0x1000, v48
	v_or_b32_e32 v40, 0x1400, v48
	global_load_dwordx4 v[68:71], v48, s[14:15]
	global_load_dwordx4 v[64:67], v36, s[14:15]
	global_load_dwordx4 v[60:63], v37, s[14:15]
	s_nop 0
	global_load_dwordx4 v[48:51], v38, s[14:15]
	s_waitcnt lgkmcnt(1)
	v_mfma_f32_32x32x16_bf16 v[0:15], v[160:163], v[32:35], v[0:15]
	s_waitcnt lgkmcnt(0)
	v_mfma_f32_32x32x16_bf16 v[16:31], v[228:231], v[32:35], v[16:31]
	ds_read_b128 v[52:55], v76
	global_load_dwordx4 v[44:47], v39, s[14:15]
	s_nop 0
	global_load_dwordx4 v[40:43], v40, s[14:15]
	s_nop 0
	global_load_dwordx4 v[36:39], v56, s[14:15]
	global_load_dwordx4 v[32:35], v57, s[14:15]
	ds_read_b128 v[56:59], v76 offset:16
	s_waitcnt lgkmcnt(1)
; #define LAS __attribute__((address_space(3)))
; DI unsigned cvt_pk_bf16(float lo, float hi) { unsigned r; asm volatile("v_cvt_pk_bf16_f32 %0, %1, %2" : "=v"(r) : "v"(lo), "v"(hi)); return r; }
; template <bool XW, int PASS, bool RMW> ...
;     ...
;       for (int t = 0; t < 2; ++t) {
;         const int sv = 2 * dq + t;
;         *(LAS bf16x8*)(vimg + ((cc + 1) & 1) * 16384 + et * 8192 + sv * 1024 + lane * 16) = scale_tab(vr[t], kdec + 16 * sv + 8 * h);
;         vr[t] = ldg16(vT, vaoff0 + (unsigned)cnn * 524288u + 1024u * sv);
;       }
;       LAS bf16_t* sw = Sb + (pbuf ^ 1) * SBE + (4 * h) * 264 + 32 * w + r;
; #pragma unroll
;       for (int i = 0; i < 16; ++i) {
;         const int eo = ((i & 3) + 8 * (i >> 2)) * 264;
;         const unsigned pkw = cvt_pk_bf16(st0[i], st1[i]);
;         sw[eo] = (bf16_t)(pkw & 0xffffu);
;         sw[eo + 32 * 264] = (bf16_t)(pkw >> 16);
;       }
;       lds_barrier();
;       pbuf ^= 1;
	v_mul_f32_e32 v52, v52, v82
	v_mul_f32_e32 v53, v53, v83
	v_mul_f32_e32 v54, v54, v84
	v_mul_f32_e32 v55, v55, v85
	s_waitcnt lgkmcnt(0)
	v_mul_f32_e32 v56, v56, v86
	v_mul_f32_e32 v57, v57, v87
	v_mul_f32_e32 v58, v58, v88
	v_mul_f32_e32 v59, v59, v89
	v_cvt_pk_bf16_f32 v52, v52, v53
	v_cvt_pk_bf16_f32 v53, v54, v55
	v_cvt_pk_bf16_f32 v54, v56, v57
	v_cvt_pk_bf16_f32 v55, v58, v59
	ds_write_b128 v73, v[52:55]
	global_load_dwordx4 v[56:59], v78, s[16:17]
	ds_read_b128 v[52:55], v77
	ds_read_b128 v[78:81], v77 offset:16
	s_waitcnt lgkmcnt(1)
	v_mul_f32_e32 v52, v52, v90
	v_mul_f32_e32 v53, v53, v91
	v_mul_f32_e32 v54, v54, v92
	v_mul_f32_e32 v55, v55, v93
	s_waitcnt lgkmcnt(0)
	v_mul_f32_e32 v81, v81, v97
	v_mul_f32_e32 v73, v78, v94
	v_mul_f32_e32 v82, v79, v95
	v_mul_f32_e32 v83, v80, v96
	v_cvt_pk_bf16_f32 v78, v52, v53
	v_cvt_pk_bf16_f32 v79, v54, v55
	v_cvt_pk_bf16_f32 v80, v73, v82
	v_cvt_pk_bf16_f32 v81, v83, v81
	global_load_dwordx4 v[52:55], v99, s[16:17]
	v_add_u32_e32 v82, s33, v98
	v_add_u32_e32 v73, s36, v199
	ds_write_b128 v82, v[78:81]
	v_mbcnt_lo_u32_b32 v251, -1, 0
	v_mbcnt_hi_u32_b32 v251, -1, v251
	v_and_b32_e32 v251, 1, v251
	v_sub_u32_e32 v250, 0, v251
	v_and_b32_e32 v248, 0x06060606, v250
	v_xor_b32_e32 v248, 0x05040100, v248
	v_and_b32_e32 v251, 0x107e, v250
	v_add_u32_e32 v249, v73, v251
	v_cvt_pk_bf16_f32 v232, v0, v4
	v_cvt_pk_bf16_f32 v233, v1, v5
	v_cvt_pk_bf16_f32 v234, v2, v6
	v_cvt_pk_bf16_f32 v235, v3, v7
	v_cvt_pk_bf16_f32 v236, v8, v12
	v_cvt_pk_bf16_f32 v237, v9, v13
	v_cvt_pk_bf16_f32 v238, v10, v14
	v_cvt_pk_bf16_f32 v239, v11, v15
	v_mov_b32_dpp v240, v232 quad_perm:[1,0,3,2] row_mask:0xf bank_mask:0xf
	v_mov_b32_dpp v241, v233 quad_perm:[1,0,3,2] row_mask:0xf bank_mask:0xf
	v_mov_b32_dpp v242, v234 quad_perm:[1,0,3,2] row_mask:0xf bank_mask:0xf
	v_mov_b32_dpp v243, v235 quad_perm:[1,0,3,2] row_mask:0xf bank_mask:0xf
	v_mov_b32_dpp v244, v236 quad_perm:[1,0,3,2] row_mask:0xf bank_mask:0xf
	v_mov_b32_dpp v245, v237 quad_perm:[1,0,3,2] row_mask:0xf bank_mask:0xf
	v_mov_b32_dpp v246, v238 quad_perm:[1,0,3,2] row_mask:0xf bank_mask:0xf
	v_mov_b32_dpp v247, v239 quad_perm:[1,0,3,2] row_mask:0xf bank_mask:0xf
	v_perm_b32 v240, v240, v232, v248
	v_perm_b32 v241, v241, v233, v248
	v_perm_b32 v242, v242, v234, v248
	v_perm_b32 v243, v243, v235, v248
	v_perm_b32 v244, v244, v236, v248
	v_perm_b32 v245, v245, v237, v248
	v_perm_b32 v246, v246, v238, v248
	v_perm_b32 v247, v247, v239, v248
	ds_write_b32 v249, v240 offset:0
	ds_write_b32 v249, v241 offset:528
	ds_write_b32 v249, v242 offset:1056
	ds_write_b32 v249, v243 offset:1584
	ds_write_b32 v249, v244 offset:8448
	ds_write_b32 v249, v245 offset:8976
	ds_write_b32 v249, v246 offset:9504
	ds_write_b32 v249, v247 offset:10032
	v_cvt_pk_bf16_f32 v232, v16, v20
	v_cvt_pk_bf16_f32 v233, v17, v21
	v_cvt_pk_bf16_f32 v234, v18, v22
	v_cvt_pk_bf16_f32 v235, v19, v23
	v_cvt_pk_bf16_f32 v236, v24, v28
	v_cvt_pk_bf16_f32 v237, v25, v29
	v_cvt_pk_bf16_f32 v238, v26, v30
	v_cvt_pk_bf16_f32 v239, v27, v31
	v_mov_b32_dpp v240, v232 quad_perm:[1,0,3,2] row_mask:0xf bank_mask:0xf
	v_mov_b32_dpp v241, v233 quad_perm:[1,0,3,2] row_mask:0xf bank_mask:0xf
	v_mov_b32_dpp v242, v234 quad_perm:[1,0,3,2] row_mask:0xf bank_mask:0xf
	v_mov_b32_dpp v243, v235 quad_perm:[1,0,3,2] row_mask:0xf bank_mask:0xf
	v_mov_b32_dpp v244, v236 quad_perm:[1,0,3,2] row_mask:0xf bank_mask:0xf
	v_mov_b32_dpp v245, v237 quad_perm:[1,0,3,2] row_mask:0xf bank_mask:0xf
	v_mov_b32_dpp v246, v238 quad_perm:[1,0,3,2] row_mask:0xf bank_mask:0xf
	v_mov_b32_dpp v247, v239 quad_perm:[1,0,3,2] row_mask:0xf bank_mask:0xf
	v_perm_b32 v240, v240, v232, v248
	v_perm_b32 v241, v241, v233, v248
	v_perm_b32 v242, v242, v234, v248
	v_perm_b32 v243, v243, v235, v248
	v_perm_b32 v244, v244, v236, v248
	v_perm_b32 v245, v245, v237, v248
	v_perm_b32 v246, v246, v238, v248
	v_perm_b32 v247, v247, v239, v248
	ds_write_b32 v249, v240 offset:16896
	ds_write_b32 v249, v241 offset:17424
	ds_write_b32 v249, v242 offset:17952
	ds_write_b32 v249, v243 offset:18480
	ds_write_b32 v249, v244 offset:25344
	ds_write_b32 v249, v245 offset:25872
	ds_write_b32 v249, v246 offset:26400
	ds_write_b32 v249, v247 offset:26928
	s_waitcnt lgkmcnt(0)
	s_barrier
	s_mov_b32 s36, s2
	s_cbranch_scc0 .LBB0_84

; #define LAS __attribute__((address_space(3)))
; #define MFMA32(a, b, c) __builtin_amdgcn_mfma_f32_32x32x16_bf16((a), (b), (c), 0, 0, 0)
; template <bool XW, int PASS, bool RMW> ...
;     ...
;         const LAS bf16_t* sp = Sb + pbuf * SBE + r * 264 + 8 * h;
; #pragma unroll
;         for (int sb = 0; sb < 8; ++sb) {
;           bf16x8 a0[2], a1[2];
; #pragma unroll
;           for (int k = 0; k < 2; ++k) { a0[k] = *(const LAS bf16x8*)(sp + 16 * (2 * sb + k)); a1[k] = *(const LAS bf16x8*)(sp + 32 * 264 + 16 * (2 * sb + k)); }
; #pragma unroll
;           for (int k = 0; k < 2; ++k) { yc0 = MFMA32(a0[k], qf[2 * sb + k], yc0); yc1 = MFMA32(a1[k], qf[2 * sb + k], yc1); }
;         }
;         asm volatile("" : "+v"(yc0), "+v"(yc1) :: "memory");
; #pragma unroll
;         for (int s = 0; s < 16; ++s) qf[s] = ldg16(qr, qoff0 + (unsigned)cn * 262144u + 1024u * s);
.LBB0_97:
	s_mul_i32 s8, s0, 0x8400
	v_add_u32_e32 v174, s8, v217
	ds_read_b128 v[232:235], v174
	ds_read_b128 v[236:239], v174 offset:16896
	ds_read_b128 v[240:243], v174 offset:32
	ds_read_b128 v[244:247], v174 offset:16928
	ds_read_b128 v[248:251], v174 offset:64
	s_add_i32 s8, s9, 1
	v_mov_b32_e32 v169, v168
	s_and_b32 s34, s1, 0x4000
	s_waitcnt vmcnt(33)
	s_waitcnt lgkmcnt(4)
	v_mfma_f32_32x32x16_bf16 v[48:63], v[232:235], v[128:131], 0
	ds_read_b128 v[232:235], v174 offset:16960
	s_min_u32 s35, s8, s5
	v_mul_f32_e64 v30, v168, v30
	v_mul_f32_e64 v31, v169, v31
	v_pk_mul_f32 v[28:29], v[168:169], v[28:29]
	v_pk_mul_f32 v[26:27], v[168:169], v[26:27]
	v_pk_mul_f32 v[24:25], v[168:169], v[24:25]
	v_pk_mul_f32 v[22:23], v[168:169], v[22:23]
	s_waitcnt lgkmcnt(4)
	v_mfma_f32_32x32x16_bf16 v[32:47], v[236:239], v[128:131], 0
	ds_read_b128 v[236:239], v174 offset:96
	ds_read_b128 v[128:131], v174 offset:16992
	v_mul_f32_e64 v20, v168, v20
	v_mul_f32_e64 v21, v169, v21
	v_mul_f32_e64 v18, v168, v18
	v_mul_f32_e64 v19, v169, v19
	v_mul_f32_e64 v14, v168, v14
	v_mul_f32_e64 v15, v169, v15
	v_pk_mul_f32 v[12:13], v[168:169], v[12:13]
	v_pk_mul_f32 v[10:11], v[168:169], v[10:11]
	v_pk_mul_f32 v[8:9], v[168:169], v[8:9]
	v_pk_mul_f32 v[6:7], v[168:169], v[6:7]
	s_waitcnt vmcnt(32)
	s_waitcnt lgkmcnt(5)
	v_mfma_f32_32x32x16_bf16 v[48:63], v[240:243], v[124:127], v[48:63]
	ds_read_b128 v[240:243], v174 offset:128
	v_mul_f32_e64 v4, v168, v4
	v_mul_f32_e64 v5, v169, v5
	v_mul_f32_e64 v2, v168, v2
	v_mul_f32_e64 v3, v169, v3
	v_add_u32_e32 v169, s34, v218
	s_lshl_b32 s34, s35, 18
	v_add_u32_e32 v175, 0xffffff90, v173
	v_pk_mul_f32 v[16:17], v[170:171], v[16:17]
	v_pk_mul_f32 v[0:1], v[170:171], v[0:1]
	s_waitcnt lgkmcnt(5)
	v_mfma_f32_32x32x16_bf16 v[32:47], v[244:247], v[124:127], v[32:47]
	ds_read_b128 v[244:247], v174 offset:17024
	ds_read_b128 v[124:127], v174 offset:160
	v_add_u32_e32 v184, -16, v173
	v_subrev_u32_e32 v185, 64, v173
	s_addk_i32 s1, 0x4000
	s_add_i32 s9, s9, 2
	s_and_b32 s35, s1, 0x4000
	s_min_u32 s9, s9, s5
	s_waitcnt vmcnt(31)
	s_waitcnt lgkmcnt(6)
	v_mfma_f32_32x32x16_bf16 v[48:63], v[248:251], v[120:123], v[48:63]
	ds_read_b128 v[248:251], v174 offset:17056
	s_xor_b32 s0, s0, 1
	s_cmp_lg_u32 s4, s8
	s_waitcnt lgkmcnt(6)
	v_mfma_f32_32x32x16_bf16 v[32:47], v[232:235], v[120:123], v[32:47]
	ds_read_b128 v[232:235], v174 offset:192
	ds_read_b128 v[120:123], v174 offset:17088
	s_waitcnt vmcnt(30)
	s_waitcnt lgkmcnt(7)
	v_mfma_f32_32x32x16_bf16 v[48:63], v[236:239], v[116:119], v[48:63]
	ds_read_b128 v[236:239], v174 offset:224
	s_waitcnt lgkmcnt(7)
	v_mfma_f32_32x32x16_bf16 v[32:47], v[128:131], v[116:119], v[32:47]
	ds_read_b128 v[128:131], v174 offset:17120
	v_subrev_u32_e32 v178, 48, v173
	v_add_u32_e32 v179, 0xffffffa0, v173
	v_subrev_u32_e32 v180, 32, v173
	v_add_u32_e32 v181, 0xffffffb0, v173
	s_waitcnt vmcnt(29)
	s_waitcnt lgkmcnt(7)
	v_mfma_f32_32x32x16_bf16 v[48:63], v[240:243], v[112:115], v[48:63]
	ds_read_b128 v[240:243], v174 offset:256
	s_waitcnt lgkmcnt(7)
	v_mfma_f32_32x32x16_bf16 v[32:47], v[244:247], v[112:115], v[32:47]
	ds_read_b128 v[244:247], v174 offset:17152
	s_waitcnt vmcnt(28)
	s_waitcnt lgkmcnt(7)
	v_mfma_f32_32x32x16_bf16 v[48:63], v[124:127], v[108:111], v[48:63]
	ds_read_b128 v[124:127], v174 offset:288
	s_waitcnt lgkmcnt(7)
	v_mfma_f32_32x32x16_bf16 v[32:47], v[248:251], v[108:111], v[32:47]
	ds_read_b128 v[248:251], v174 offset:17184
	s_waitcnt vmcnt(27)
	s_waitcnt lgkmcnt(7)
	v_mfma_f32_32x32x16_bf16 v[48:63], v[232:235], v[104:107], v[48:63]
	ds_read_b128 v[232:235], v174 offset:320
	s_waitcnt lgkmcnt(7)
	v_mfma_f32_32x32x16_bf16 v[32:47], v[120:123], v[104:107], v[32:47]
	ds_read_b128 v[120:123], v174 offset:17216
	s_waitcnt vmcnt(26)
	s_waitcnt lgkmcnt(7)
	v_mfma_f32_32x32x16_bf16 v[48:63], v[236:239], v[100:103], v[48:63]
	ds_read_b128 v[236:239], v174 offset:352
	s_waitcnt lgkmcnt(7)
	v_mfma_f32_32x32x16_bf16 v[32:47], v[128:131], v[100:103], v[32:47]
	ds_read_b128 v[128:131], v174 offset:17248
	s_waitcnt vmcnt(25)
	s_waitcnt lgkmcnt(7)
	v_mfma_f32_32x32x16_bf16 v[48:63], v[240:243], v[96:99], v[48:63]
	ds_read_b128 v[240:243], v174 offset:384
	s_waitcnt lgkmcnt(7)
	v_mfma_f32_32x32x16_bf16 v[32:47], v[244:247], v[96:99], v[32:47]
	ds_read_b128 v[244:247], v174 offset:17280
	s_waitcnt vmcnt(24)
	s_waitcnt lgkmcnt(7)
	v_mfma_f32_32x32x16_bf16 v[48:63], v[124:127], v[92:95], v[48:63]
	ds_read_b128 v[124:127], v174 offset:416
	s_waitcnt lgkmcnt(7)
	v_mfma_f32_32x32x16_bf16 v[32:47], v[248:251], v[92:95], v[32:47]
	ds_read_b128 v[248:251], v174 offset:17312
	s_waitcnt vmcnt(23)
	s_waitcnt lgkmcnt(7)
	v_mfma_f32_32x32x16_bf16 v[48:63], v[232:235], v[88:91], v[48:63]
	ds_read_b128 v[232:235], v174 offset:448
	s_waitcnt lgkmcnt(7)
	v_mfma_f32_32x32x16_bf16 v[32:47], v[120:123], v[88:91], v[32:47]
	ds_read_b128 v[120:123], v174 offset:17344
	s_waitcnt vmcnt(22)
	s_waitcnt lgkmcnt(7)
	v_mfma_f32_32x32x16_bf16 v[48:63], v[236:239], v[80:83], v[48:63]
	ds_read_b128 v[236:239], v174 offset:480
	s_waitcnt lgkmcnt(7)
	v_mfma_f32_32x32x16_bf16 v[32:47], v[128:131], v[80:83], v[32:47]
	ds_read_b128 v[128:131], v174 offset:17376
	s_waitcnt vmcnt(21)
	s_waitcnt lgkmcnt(7)
	v_mfma_f32_32x32x16_bf16 v[48:63], v[240:243], v[76:79], v[48:63]
	s_waitcnt lgkmcnt(6)
	v_mfma_f32_32x32x16_bf16 v[32:47], v[244:247], v[76:79], v[32:47]
	s_waitcnt vmcnt(20)
	s_waitcnt lgkmcnt(5)
	v_mfma_f32_32x32x16_bf16 v[48:63], v[124:127], v[72:75], v[48:63]
	v_add_u32_e32 v88, s34, v226
	v_or_b32_e32 v89, 0x400, v88
	v_or_b32_e32 v186, 0x3800, v88
	v_or_b32_e32 v187, 0x3c00, v88
	s_waitcnt lgkmcnt(4)
; #define LAS __attribute__((address_space(3)))
; DI unsigned cvt_pk_bf16(float lo, float hi) { unsigned r; asm volatile("v_cvt_pk_bf16_f32 %0, %1, %2" : "=v"(r) : "v"(lo), "v"(hi)); return r; }
; DI float bf_lo(unsigned w) { return __uint_as_float(w << 16); }
; DI float bf_hi(unsigned w) { return __uint_as_float(w & 0xffff0000u); }
; #define MFMA32(a, b, c) __builtin_amdgcn_mfma_f32_32x32x16_bf16((a), (b), (c), 0, 0, 0)
; template <bool XW, int PASS, bool RMW> ...
;     ...
;         for (int s = 0; s < 16; ++s) qf[s] = ldg16(qr, qoff0 + (unsigned)cn * 262144u + 1024u * s);
;         const float qe = cc > 0 ? qd : 0.f;
; #pragma unroll
;         for (int gq = 0; gq < 4; ++gq) {
;           u32x2 a; a.x = cvt_pk_bf16(bf_lo(ovn[gq].x) + qe * yc0[4 * gq], bf_hi(ovn[gq].x) + qe * yc0[4 * gq + 1]); a.y = cvt_pk_bf16(bf_lo(ovn[gq].y) + qe * yc0[4 * gq + 2], bf_hi(ovn[gq].y) + qe * yc0[4 * gq + 3]);
;           *(u32x2*)((char*)y + (yb + 16u * gq)) = a;
;           u32x2 c2; c2.x = cvt_pk_bf16(bf_lo(ovn[4 + gq].x) + qe * yc1[4 * gq], bf_hi(ovn[4 + gq].x) + qe * yc1[4 * gq + 1]); c2.y = cvt_pk_bf16(bf_lo(ovn[4 + gq].y) + qe * yc1[4 * gq + 2], bf_hi(ovn[4 + gq].y) + qe * yc1[4 * gq + 3]);
;           *(u32x2*)((char*)y + (yb + 64u + 16u * gq)) = c2;
;         }
;         if constexpr (PASS == 1 && RMW) {
;           const unsigned ybn = yoff0 + (unsigned)cn * 524288u;
; #pragma unroll
;           for (int gq = 0; gq < 8; ++gq) ovn[gq] = *(const u32x2*)((const char*)y + (ybn + 64u * (gq >> 2) + 16u * (gq & 3)));
;         }
;       }
; #pragma unroll
;       for (int i = 0; i < 16; ++i) { st0[i] *= cd; st1[i] *= cd; }
; #pragma unroll
;       for (int sb = 0; sb < 2; ++sb) {
;         bf16x8 a0[4], a1[4];
; #pragma unroll
;         for (int k = 0; k < 4; ++k) { a0[k] = *(const LAS bf16x8*)(vimg + (cc & 1) * 16384 + (4 * sb + k) * 1024 + lane * 16); a1[k] = *(const LAS bf16x8*)(vimg + (cc & 1) * 16384 + 8192 + (4 * sb + k) * 1024 + lane * 16); }
; #pragma unroll
;         for (int k = 0; k < 4; ++k) { st0 = MFMA32(a0[k], kb0[4 * sb + k], st0); st1 = MFMA32(a1[k], kb0[4 * sb + k], st1); }
;         asm volatile("" : "+v"(st0), "+v"(st1) :: "memory");
; #pragma unroll
;         for (int k = 0; k < 4; ++k) kb0[4 * sb + k] = ldg16(kT, kboff0 + (unsigned)cn * 262144u + 1024u * (4 * sb + k));
	v_mfma_f32_32x32x16_bf16 v[32:47], v[248:251], v[72:75], v[32:47]
	s_waitcnt vmcnt(19)
	s_waitcnt lgkmcnt(3)
	v_mfma_f32_32x32x16_bf16 v[48:63], v[232:235], v[68:71], v[48:63]
	v_or_b32_e32 v174, 0x3400, v88
	s_waitcnt lgkmcnt(2)
	v_mfma_f32_32x32x16_bf16 v[32:47], v[120:123], v[68:71], v[32:47]
	v_or_b32_e32 v68, 0x800, v88
	v_or_b32_e32 v69, 0xc00, v88
	v_or_b32_e32 v70, 0x1000, v88
	v_or_b32_e32 v71, 0x1400, v88
	v_or_b32_e32 v72, 0x1800, v88
	v_or_b32_e32 v73, 0x1c00, v88
	v_or_b32_e32 v74, 0x2000, v88
	s_waitcnt vmcnt(18)
	s_waitcnt lgkmcnt(1)
	v_mfma_f32_32x32x16_bf16 v[48:63], v[236:239], v[64:67], v[48:63]
	v_or_b32_e32 v75, 0x2400, v88
	v_or_b32_e32 v76, 0x2800, v88
	v_or_b32_e32 v77, 0x2c00, v88
	v_or_b32_e32 v78, 0x3000, v88
	s_waitcnt lgkmcnt(0)
	v_mfma_f32_32x32x16_bf16 v[32:47], v[128:131], v[64:67], v[32:47]
	global_load_dwordx4 v[128:131], v88, s[92:93]
	global_load_dwordx4 v[124:127], v89, s[92:93]
	global_load_dwordx4 v[120:123], v68, s[92:93]
	global_load_dwordx4 v[116:119], v69, s[92:93]
	global_load_dwordx4 v[112:115], v70, s[92:93]
	global_load_dwordx4 v[108:111], v71, s[92:93]
	global_load_dwordx4 v[104:107], v72, s[92:93]
	global_load_dwordx4 v[100:103], v73, s[92:93]
	global_load_dwordx4 v[96:99], v74, s[92:93]
	global_load_dwordx4 v[92:95], v75, s[92:93]
	global_load_dwordx4 v[88:91], v76, s[92:93]
	global_load_dwordx4 v[80:83], v77, s[92:93]
	s_nop 0
	global_load_dwordx4 v[76:79], v78, s[92:93]
	s_nop 0
	global_load_dwordx4 v[72:75], v174, s[92:93]
	global_load_dwordx4 v[68:71], v186, s[92:93]
	global_load_dwordx4 v[64:67], v187, s[92:93]
	v_fma_f32 v48, v172, v48, 0
	v_fma_f32 v49, v172, v49, 0
	v_fma_f32 v50, v172, v50, 0
	v_fma_f32 v51, v172, v51, 0
	v_fma_f32 v174, v172, v32, 0
	v_fma_f32 v186, v172, v33, 0
	v_cvt_pk_bf16_f32 v32, v48, v49
	v_cvt_pk_bf16_f32 v33, v50, v51
	v_fma_f32 v34, v172, v34, 0
	v_fma_f32 v35, v172, v35, 0
	global_store_dwordx2 v175, v[32:33], s[18:19]
	v_cvt_pk_bf16_f32 v32, v174, v186
	v_cvt_pk_bf16_f32 v33, v34, v35
	v_fma_f32 v52, v172, v52, 0
	v_fma_f32 v53, v172, v53, 0
	v_fma_f32 v54, v172, v54, 0
	v_fma_f32 v55, v172, v55, 0
	global_store_dwordx2 v178, v[32:33], s[18:19]
	v_cvt_pk_bf16_f32 v32, v52, v53
	v_cvt_pk_bf16_f32 v33, v54, v55
	v_fma_f32 v36, v172, v36, 0
	v_fma_f32 v37, v172, v37, 0
	v_fma_f32 v38, v172, v38, 0
	v_fma_f32 v39, v172, v39, 0
	global_store_dwordx2 v179, v[32:33], s[18:19]
	v_cvt_pk_bf16_f32 v32, v36, v37
	v_cvt_pk_bf16_f32 v33, v38, v39
	v_fma_f32 v56, v172, v56, 0
	v_fma_f32 v57, v172, v57, 0
	v_fma_f32 v58, v172, v58, 0
	v_fma_f32 v59, v172, v59, 0
	global_store_dwordx2 v180, v[32:33], s[18:19]
	v_cvt_pk_bf16_f32 v32, v56, v57
	v_cvt_pk_bf16_f32 v33, v58, v59
	v_fma_f32 v40, v172, v40, 0
	v_fma_f32 v41, v172, v41, 0
	v_fma_f32 v42, v172, v42, 0
	v_fma_f32 v43, v172, v43, 0
	global_store_dwordx2 v181, v[32:33], s[18:19]
	v_cvt_pk_bf16_f32 v32, v40, v41
	v_cvt_pk_bf16_f32 v33, v42, v43
	v_fma_f32 v60, v172, v60, 0
	v_fma_f32 v61, v172, v61, 0
	v_fma_f32 v62, v172, v62, 0
	v_fma_f32 v63, v172, v63, 0
	v_fma_f32 v44, v172, v44, 0
	v_fma_f32 v45, v172, v45, 0
	global_store_dwordx2 v184, v[32:33], s[18:19]
	v_cvt_pk_bf16_f32 v32, v60, v61
	v_cvt_pk_bf16_f32 v33, v62, v63
	v_fma_f32 v46, v172, v46, 0
	v_fma_f32 v47, v172, v47, 0
	global_store_dwordx2 v185, v[32:33], s[18:19]
	v_cvt_pk_bf16_f32 v44, v44, v45
	v_cvt_pk_bf16_f32 v45, v46, v47
	ds_read_b128 v[232:235], v169
	ds_read_b128 v[236:239], v169 offset:8192
	ds_read_b128 v[240:243], v169 offset:1024
	ds_read_b128 v[244:247], v169 offset:9216
	ds_read_b128 v[248:251], v169 offset:2048
	s_waitcnt vmcnt(32)
	s_waitcnt lgkmcnt(4)
	v_mfma_f32_32x32x16_bf16 v[16:31], v[232:235], v[164:167], v[16:31]
	ds_read_b128 v[232:235], v169 offset:10240
	v_add_u32_e32 v62, s34, v223
	s_waitcnt vmcnt(24)
	v_lshlrev_b32_e32 v46, 16, v152
	v_and_b32_e32 v47, 0xffff0000, v152
	v_lshlrev_b32_e32 v48, 16, v153
	v_and_b32_e32 v49, 0xffff0000, v153
	v_add_u32_e32 v60, s35, v198
	s_waitcnt lgkmcnt(4)
	v_mfma_f32_32x32x16_bf16 v[0:15], v[236:239], v[164:167], v[0:15]
	ds_read_b128 v[236:239], v169 offset:3072
	v_lshlrev_b32_e32 v50, 16, v154
	v_and_b32_e32 v51, 0xffff0000, v154
	v_lshlrev_b32_e32 v52, 16, v155
	v_lshl_add_u32 v61, s9, 19, v224
	v_add_u32_e32 v63, s3, v60
	s_waitcnt vmcnt(23)
	v_and_b32_e32 v53, 0xffff0000, v148
	v_lshlrev_b32_e32 v54, 16, v149
	s_waitcnt lgkmcnt(4)
	v_mfma_f32_32x32x16_bf16 v[16:31], v[240:243], v[160:163], v[16:31]
	ds_read_b128 v[240:243], v169 offset:11264
	v_and_b32_e32 v55, 0xffff0000, v149
	v_lshlrev_b32_e32 v56, 16, v150
	v_and_b32_e32 v57, 0xffff0000, v150
	v_lshlrev_b32_e32 v58, 16, v151
	v_and_b32_e32 v59, 0xffff0000, v151
	s_mul_i32 s9, s0, 0x8400
	s_waitcnt lgkmcnt(4)
	v_mfma_f32_32x32x16_bf16 v[0:15], v[244:247], v[160:163], v[0:15]
	ds_read_b128 v[244:247], v169 offset:4096
	s_waitcnt lgkmcnt(4)
	v_mfma_f32_32x32x16_bf16 v[16:31], v[248:251], v[156:159], v[16:31]
	ds_read_b128 v[248:251], v169 offset:12288
	global_store_dwordx2 v173, v[44:45], s[18:19]
	v_and_b32_e32 v44, 0xffff0000, v155
	v_lshlrev_b32_e32 v45, 16, v148
	v_or_b32_e32 v148, s3, v61
	v_or_b32_e32 v61, s33, v61
	v_add_u32_e32 v173, 0x80000, v173
	s_waitcnt lgkmcnt(4)
	v_mfma_f32_32x32x16_bf16 v[0:15], v[232:235], v[156:159], v[0:15]
	ds_read_b128 v[232:235], v169 offset:5120
	s_waitcnt lgkmcnt(4)
	v_mfma_f32_32x32x16_bf16 v[16:31], v[236:239], v[140:143], v[16:31]
	ds_read_b128 v[236:239], v169 offset:13312
	s_waitcnt lgkmcnt(4)
	v_mfma_f32_32x32x16_bf16 v[0:15], v[240:243], v[140:143], v[0:15]
	ds_read_b128 v[240:243], v169 offset:6144
	s_waitcnt lgkmcnt(4)
; #define LAS __attribute__((address_space(3)))
; DI unsigned cvt_pk_bf16(float lo, float hi) { unsigned r; asm volatile("v_cvt_pk_bf16_f32 %0, %1, %2" : "=v"(r) : "v"(lo), "v"(hi)); return r; }
; #define MFMA32(a, b, c) __builtin_amdgcn_mfma_f32_32x32x16_bf16((a), (b), (c), 0, 0, 0)
; template <bool XW, int PASS, bool RMW> ...
;     ...
;       for (int sb = 0; sb < 2; ++sb) {
;         bf16x8 a0[4], a1[4];
; #pragma unroll
;         for (int k = 0; k < 4; ++k) { a0[k] = *(const LAS bf16x8*)(vimg + (cc & 1) * 16384 + (4 * sb + k) * 1024 + lane * 16); a1[k] = *(const LAS bf16x8*)(vimg + (cc & 1) * 16384 + 8192 + (4 * sb + k) * 1024 + lane * 16); }
; #pragma unroll
;         for (int k = 0; k < 4; ++k) { st0 = MFMA32(a0[k], kb0[4 * sb + k], st0); st1 = MFMA32(a1[k], kb0[4 * sb + k], st1); }
;         asm volatile("" : "+v"(st0), "+v"(st1) :: "memory");
; #pragma unroll
;         for (int k = 0; k < 4; ++k) kb0[4 * sb + k] = ldg16(kT, kboff0 + (unsigned)cn * 262144u + 1024u * (4 * sb + k));
;       }
; #pragma unroll
;       for (int t = 0; t < 2; ++t) {
;         const int sv = 2 * dq + t;
;         *(LAS bf16x8*)(vimg + ((cc + 1) & 1) * 16384 + et * 8192 + sv * 1024 + lane * 16) = scale_tab(vr[t], kdec + 16 * sv + 8 * h);
;         vr[t] = ldg16(vT, vaoff0 + (unsigned)cnn * 524288u + 1024u * sv);
;       }
;       LAS bf16_t* sw = Sb + (pbuf ^ 1) * SBE + (4 * h) * 264 + 32 * w + r;
; #pragma unroll
;       for (int i = 0; i < 16; ++i) {
;         const int eo = ((i & 3) + 8 * (i >> 2)) * 264;
;         const unsigned pkw = cvt_pk_bf16(st0[i], st1[i]);
;         sw[eo] = (bf16_t)(pkw & 0xffffu);
;         sw[eo + 32 * 264] = (bf16_t)(pkw >> 16);
;       }
;       lds_barrier();
;       pbuf ^= 1;
	v_mfma_f32_32x32x16_bf16 v[16:31], v[244:247], v[144:147], v[16:31]
	ds_read_b128 v[244:247], v169 offset:14336
	s_waitcnt lgkmcnt(4)
	v_mfma_f32_32x32x16_bf16 v[0:15], v[248:251], v[144:147], v[0:15]
	ds_read_b128 v[248:251], v169 offset:7168
	s_waitcnt lgkmcnt(4)
	v_mfma_f32_32x32x16_bf16 v[16:31], v[232:235], v[136:139], v[16:31]
	ds_read_b128 v[232:235], v169 offset:15360
	s_waitcnt lgkmcnt(4)
	v_mfma_f32_32x32x16_bf16 v[0:15], v[236:239], v[136:139], v[0:15]
	s_waitcnt lgkmcnt(3)
	v_mfma_f32_32x32x16_bf16 v[16:31], v[240:243], v[132:135], v[16:31]
	s_waitcnt lgkmcnt(2)
	v_mfma_f32_32x32x16_bf16 v[0:15], v[244:247], v[132:135], v[0:15]
	v_or_b32_e32 v32, 0x400, v62
	v_or_b32_e32 v33, 0x800, v62
	v_or_b32_e32 v34, 0xc00, v62
	global_load_dwordx4 v[164:167], v62, s[14:15]
	global_load_dwordx4 v[160:163], v32, s[14:15]
	global_load_dwordx4 v[156:159], v33, s[14:15]
	global_load_dwordx4 v[140:143], v34, s[14:15]
	v_or_b32_e32 v132, 0x1000, v62
	s_waitcnt lgkmcnt(1)
	v_mfma_f32_32x32x16_bf16 v[16:31], v[248:251], v[84:87], v[16:31]
	v_or_b32_e32 v36, 0x1400, v62
	v_or_b32_e32 v37, 0x1800, v62
	v_or_b32_e32 v38, 0x1c00, v62
	s_waitcnt lgkmcnt(0)
	v_mfma_f32_32x32x16_bf16 v[0:15], v[232:235], v[84:87], v[0:15]
	ds_read_b128 v[32:35], v228
	global_load_dwordx4 v[144:147], v132, s[14:15]
	global_load_dwordx4 v[136:139], v36, s[14:15]
	s_nop 0
	global_load_dwordx4 v[132:135], v37, s[14:15]
	global_load_dwordx4 v[84:87], v38, s[14:15]
	ds_read_b128 v[36:39], v228 offset:16
	s_waitcnt lgkmcnt(1)
	v_mul_f32_e32 v32, v32, v46
	v_mul_f32_e32 v33, v33, v47
	v_mul_f32_e32 v34, v34, v48
	v_mul_f32_e32 v35, v35, v49
	s_waitcnt lgkmcnt(0)
	v_mul_f32_e32 v36, v36, v50
	v_mul_f32_e32 v37, v37, v51
	v_mul_f32_e32 v38, v38, v52
	v_mul_f32_e32 v39, v39, v44
	v_cvt_pk_bf16_f32 v32, v32, v33
	v_cvt_pk_bf16_f32 v33, v34, v35
	v_cvt_pk_bf16_f32 v34, v36, v37
	v_cvt_pk_bf16_f32 v35, v38, v39
	ds_write_b128 v63, v[32:35]
	global_load_dwordx4 v[152:155], v148, s[16:17]
	ds_read_b128 v[32:35], v229
	ds_read_b128 v[36:39], v229 offset:16
	s_waitcnt lgkmcnt(1)
	v_mul_f32_e32 v32, v32, v45
	v_mul_f32_e32 v33, v33, v53
	v_mul_f32_e32 v34, v34, v54
	v_mul_f32_e32 v35, v35, v55
	s_waitcnt lgkmcnt(0)
	v_mul_f32_e32 v36, v36, v56
	v_mul_f32_e32 v37, v37, v57
	v_mul_f32_e32 v38, v38, v58
	v_mul_f32_e32 v39, v39, v59
	v_cvt_pk_bf16_f32 v32, v32, v33
	v_cvt_pk_bf16_f32 v33, v34, v35
	v_cvt_pk_bf16_f32 v34, v36, v37
	v_cvt_pk_bf16_f32 v35, v38, v39
	global_load_dwordx4 v[148:151], v61, s[16:17]
	v_add_u32_e32 v37, s33, v60
	v_add_u32_e32 v36, s9, v199
	ds_write_b128 v37, v[32:35]
	v_mbcnt_lo_u32_b32 v251, -1, 0
	v_mbcnt_hi_u32_b32 v251, -1, v251
	v_and_b32_e32 v251, 1, v251
	v_sub_u32_e32 v250, 0, v251
	v_and_b32_e32 v248, 0x06060606, v250
	v_xor_b32_e32 v248, 0x05040100, v248
	v_and_b32_e32 v251, 0x107e, v250
	v_add_u32_e32 v249, v36, v251
	v_cvt_pk_bf16_f32 v232, v16, v20
	v_cvt_pk_bf16_f32 v233, v17, v21
	v_cvt_pk_bf16_f32 v234, v18, v22
	v_cvt_pk_bf16_f32 v235, v19, v23
	v_cvt_pk_bf16_f32 v236, v24, v28
	v_cvt_pk_bf16_f32 v237, v25, v29
	v_cvt_pk_bf16_f32 v238, v26, v30
	v_cvt_pk_bf16_f32 v239, v27, v31
	v_mov_b32_dpp v240, v232 quad_perm:[1,0,3,2] row_mask:0xf bank_mask:0xf
	v_mov_b32_dpp v241, v233 quad_perm:[1,0,3,2] row_mask:0xf bank_mask:0xf
	v_mov_b32_dpp v242, v234 quad_perm:[1,0,3,2] row_mask:0xf bank_mask:0xf
	v_mov_b32_dpp v243, v235 quad_perm:[1,0,3,2] row_mask:0xf bank_mask:0xf
	v_mov_b32_dpp v244, v236 quad_perm:[1,0,3,2] row_mask:0xf bank_mask:0xf
	v_mov_b32_dpp v245, v237 quad_perm:[1,0,3,2] row_mask:0xf bank_mask:0xf
	v_mov_b32_dpp v246, v238 quad_perm:[1,0,3,2] row_mask:0xf bank_mask:0xf
	v_mov_b32_dpp v247, v239 quad_perm:[1,0,3,2] row_mask:0xf bank_mask:0xf
	v_perm_b32 v240, v240, v232, v248
	v_perm_b32 v241, v241, v233, v248
	v_perm_b32 v242, v242, v234, v248
	v_perm_b32 v243, v243, v235, v248
	v_perm_b32 v244, v244, v236, v248
	v_perm_b32 v245, v245, v237, v248
	v_perm_b32 v246, v246, v238, v248
	v_perm_b32 v247, v247, v239, v248
	ds_write_b32 v249, v240 offset:0
	ds_write_b32 v249, v241 offset:528
	ds_write_b32 v249, v242 offset:1056
	ds_write_b32 v249, v243 offset:1584
	ds_write_b32 v249, v244 offset:8448
	ds_write_b32 v249, v245 offset:8976
	ds_write_b32 v249, v246 offset:9504
	ds_write_b32 v249, v247 offset:10032
	v_cvt_pk_bf16_f32 v232, v0, v4
	v_cvt_pk_bf16_f32 v233, v1, v5
	v_cvt_pk_bf16_f32 v234, v2, v6
	v_cvt_pk_bf16_f32 v235, v3, v7
	v_cvt_pk_bf16_f32 v236, v8, v12
	v_cvt_pk_bf16_f32 v237, v9, v13
	v_cvt_pk_bf16_f32 v238, v10, v14
	v_cvt_pk_bf16_f32 v239, v11, v15
	v_mov_b32_dpp v240, v232 quad_perm:[1,0,3,2] row_mask:0xf bank_mask:0xf
	v_mov_b32_dpp v241, v233 quad_perm:[1,0,3,2] row_mask:0xf bank_mask:0xf
	v_mov_b32_dpp v242, v234 quad_perm:[1,0,3,2] row_mask:0xf bank_mask:0xf
	v_mov_b32_dpp v243, v235 quad_perm:[1,0,3,2] row_mask:0xf bank_mask:0xf
	v_mov_b32_dpp v244, v236 quad_perm:[1,0,3,2] row_mask:0xf bank_mask:0xf
	v_mov_b32_dpp v245, v237 quad_perm:[1,0,3,2] row_mask:0xf bank_mask:0xf
	v_mov_b32_dpp v246, v238 quad_perm:[1,0,3,2] row_mask:0xf bank_mask:0xf
	v_mov_b32_dpp v247, v239 quad_perm:[1,0,3,2] row_mask:0xf bank_mask:0xf
	v_perm_b32 v240, v240, v232, v248
	v_perm_b32 v241, v241, v233, v248
	v_perm_b32 v242, v242, v234, v248
	v_perm_b32 v243, v243, v235, v248
	v_perm_b32 v244, v244, v236, v248
	v_perm_b32 v245, v245, v237, v248
	v_perm_b32 v246, v246, v238, v248
	v_perm_b32 v247, v247, v239, v248
	ds_write_b32 v249, v240 offset:16896
	ds_write_b32 v249, v241 offset:17424
	ds_write_b32 v249, v242 offset:17952
	ds_write_b32 v249, v243 offset:18480
	ds_write_b32 v249, v244 offset:25344
	ds_write_b32 v249, v245 offset:25872
	ds_write_b32 v249, v246 offset:26400
	ds_write_b32 v249, v247 offset:26928
	s_waitcnt lgkmcnt(0)
	s_barrier
	s_mov_b32 s9, s8
	s_cbranch_scc1 .LBB0_97
	s_cmp_lg_u32 s31, 0
	s_cbranch_scc1 .LBB0_103
	s_and_saveexec_b64 s[0:1], s[6:7]
	s_cbranch_execz .LBB0_101
	v_mul_f32_e64 v0, v200, -v225
	v_exp_f32_e32 v0, v0
	ds_write_b32 v195, v0

; #define LAS __attribute__((address_space(3)))
; DI unsigned cvt_pk_bf16(float lo, float hi) { unsigned r; asm volatile("v_cvt_pk_bf16_f32 %0, %1, %2" : "=v"(r) : "v"(lo), "v"(hi)); return r; }
; DI float bf_lo(unsigned w) { return __uint_as_float(w << 16); }
; DI float bf_hi(unsigned w) { return __uint_as_float(w & 0xffff0000u); }
; #define MFMA32(a, b, c) __builtin_amdgcn_mfma_f32_32x32x16_bf16((a), (b), (c), 0, 0, 0)
; template <bool XW, int PASS, bool RMW> ...
;     ...
;       if constexpr (XW) {
;         const unsigned yb = yoff0 + (unsigned)c * 524288u;
;         f32x16 yc0, yc1;
; #pragma unroll
;         for (int i = 0; i < 16; ++i) { yc0[i] = 0.f; yc1[i] = 0.f; }
;         const LAS bf16_t* sp = Sb + pbuf * SBE + r * 264 + 8 * h;
; #pragma unroll
;         for (int sb = 0; sb < 8; ++sb) {
;           bf16x8 a0[2], a1[2];
; #pragma unroll
;           for (int k = 0; k < 2; ++k) { a0[k] = *(const LAS bf16x8*)(sp + 16 * (2 * sb + k)); a1[k] = *(const LAS bf16x8*)(sp + 32 * 264 + 16 * (2 * sb + k)); }
; #pragma unroll
;           for (int k = 0; k < 2; ++k) { yc0 = MFMA32(a0[k], qf[2 * sb + k], yc0); yc1 = MFMA32(a1[k], qf[2 * sb + k], yc1); }
;         }
;         asm volatile("" : "+v"(yc0), "+v"(yc1) :: "memory");
; #pragma unroll
;         for (int s = 0; s < 16; ++s) qf[s] = ldg16(qr, qoff0 + (unsigned)cn * 262144u + 1024u * s);
;         const float qe = cc > 0 ? qd : 0.f;
; #pragma unroll
;         for (int gq = 0; gq < 4; ++gq) {
;           u32x2 a; a.x = cvt_pk_bf16(bf_lo(ovn[gq].x) + qe * yc0[4 * gq], bf_hi(ovn[gq].x) + qe * yc0[4 * gq + 1]); a.y = cvt_pk_bf16(bf_lo(ovn[gq].y) + qe * yc0[4 * gq + 2], bf_hi(ovn[gq].y) + qe * yc0[4 * gq + 3]);
;           *(u32x2*)((char*)y + (yb + 16u * gq)) = a;
;           u32x2 c2; c2.x = cvt_pk_bf16(bf_lo(ovn[4 + gq].x) + qe * yc1[4 * gq], bf_hi(ovn[4 + gq].x) + qe * yc1[4 * gq + 1]); c2.y = cvt_pk_bf16(bf_lo(ovn[4 + gq].y) + qe * yc1[4 * gq + 2], bf_hi(ovn[4 + gq].y) + qe * yc1[4 * gq + 3]);
;           *(u32x2*)((char*)y + (yb + 64u + 16u * gq)) = c2;
;         }
.LBB0_102:
	s_add_i32 s8, s2, 1
	v_mov_b32_e32 v32, s8
	s_add_i32 s2, s2, 2
	v_sub_u32_e64 v169, s5, v32 clamp
	v_mov_b32_e32 v32, s2
	s_mul_i32 s2, s0, 0x8400
	v_add_u32_e32 v204, s2, v217
	v_sub_u32_e64 v203, s5, v32 clamp
	ds_read_b128 v[232:235], v204
	ds_read_b128 v[236:239], v204 offset:16896
	ds_read_b128 v[240:243], v204 offset:32
	ds_read_b128 v[244:247], v204 offset:16928
	ds_read_b128 v[248:251], v204 offset:64
	s_waitcnt vmcnt(41)
	s_waitcnt lgkmcnt(4)
	v_mfma_f32_32x32x16_bf16 v[48:63], v[232:235], v[120:123], 0
	ds_read_b128 v[232:235], v204 offset:16960
	v_lshlrev_b32_e32 v206, 18, v169
	s_waitcnt vmcnt(17)
	v_lshlrev_b32_e32 v205, 16, v188
	s_and_b32 s2, s1, 0x4000
	v_mul_f32_e64 v16, v182, v16
	v_mul_f32_e64 v17, v183, v17
	v_pk_mul_f32 v[0:1], v[182:183], v[0:1]
	s_addk_i32 s1, 0x4000
	s_xor_b32 s0, s0, 1
	s_waitcnt lgkmcnt(4)
	v_mfma_f32_32x32x16_bf16 v[32:47], v[236:239], v[120:123], 0
	ds_read_b128 v[236:239], v204 offset:96
	ds_read_b128 v[120:123], v204 offset:16992
	s_waitcnt lgkmcnt(5)
	v_mfma_f32_32x32x16_bf16 v[48:63], v[240:243], v[124:127], v[48:63]
	ds_read_b128 v[240:243], v204 offset:128
	s_waitcnt lgkmcnt(5)
	v_mfma_f32_32x32x16_bf16 v[32:47], v[244:247], v[124:127], v[32:47]
	ds_read_b128 v[244:247], v204 offset:17024
	ds_read_b128 v[124:127], v204 offset:160
	s_waitcnt lgkmcnt(6)
	v_mfma_f32_32x32x16_bf16 v[48:63], v[248:251], v[112:115], v[48:63]
	ds_read_b128 v[248:251], v204 offset:17056
	s_waitcnt lgkmcnt(6)
	v_mfma_f32_32x32x16_bf16 v[32:47], v[232:235], v[112:115], v[32:47]
	ds_read_b128 v[232:235], v204 offset:192
	ds_read_b128 v[112:115], v204 offset:17088
	s_waitcnt lgkmcnt(7)
	v_mfma_f32_32x32x16_bf16 v[48:63], v[236:239], v[116:119], v[48:63]
	ds_read_b128 v[236:239], v204 offset:224
	s_waitcnt lgkmcnt(7)
	v_mfma_f32_32x32x16_bf16 v[32:47], v[120:123], v[116:119], v[32:47]
	ds_read_b128 v[120:123], v204 offset:17120
	s_waitcnt lgkmcnt(7)
	v_mfma_f32_32x32x16_bf16 v[48:63], v[240:243], v[104:107], v[48:63]
	ds_read_b128 v[240:243], v204 offset:256
	s_waitcnt lgkmcnt(7)
	v_mfma_f32_32x32x16_bf16 v[32:47], v[244:247], v[104:107], v[32:47]
	ds_read_b128 v[244:247], v204 offset:17152
	s_waitcnt lgkmcnt(7)
	v_mfma_f32_32x32x16_bf16 v[48:63], v[124:127], v[108:111], v[48:63]
	ds_read_b128 v[124:127], v204 offset:288
	s_waitcnt lgkmcnt(7)
	v_mfma_f32_32x32x16_bf16 v[32:47], v[248:251], v[108:111], v[32:47]
	ds_read_b128 v[248:251], v204 offset:17184
	s_waitcnt lgkmcnt(7)
	v_mfma_f32_32x32x16_bf16 v[48:63], v[232:235], v[96:99], v[48:63]
	ds_read_b128 v[232:235], v204 offset:320
	s_waitcnt lgkmcnt(7)
	v_mfma_f32_32x32x16_bf16 v[32:47], v[112:115], v[96:99], v[32:47]
	ds_read_b128 v[112:115], v204 offset:17216
	s_waitcnt lgkmcnt(7)
	v_mfma_f32_32x32x16_bf16 v[48:63], v[236:239], v[100:103], v[48:63]
	ds_read_b128 v[236:239], v204 offset:352
	s_waitcnt lgkmcnt(7)
	v_mfma_f32_32x32x16_bf16 v[32:47], v[120:123], v[100:103], v[32:47]
	ds_read_b128 v[120:123], v204 offset:17248
	s_waitcnt lgkmcnt(7)
	v_mfma_f32_32x32x16_bf16 v[48:63], v[240:243], v[88:91], v[48:63]
	ds_read_b128 v[240:243], v204 offset:384
	s_waitcnt lgkmcnt(7)
	v_mfma_f32_32x32x16_bf16 v[32:47], v[244:247], v[88:91], v[32:47]
	ds_read_b128 v[244:247], v204 offset:17280
	s_waitcnt lgkmcnt(7)
	v_mfma_f32_32x32x16_bf16 v[48:63], v[124:127], v[92:95], v[48:63]
	ds_read_b128 v[124:127], v204 offset:416
	s_waitcnt lgkmcnt(7)
	v_mfma_f32_32x32x16_bf16 v[32:47], v[248:251], v[92:95], v[32:47]
	ds_read_b128 v[248:251], v204 offset:17312
	s_waitcnt lgkmcnt(7)
	v_mfma_f32_32x32x16_bf16 v[48:63], v[232:235], v[80:83], v[48:63]
	ds_read_b128 v[232:235], v204 offset:448
	s_waitcnt lgkmcnt(7)
	v_mfma_f32_32x32x16_bf16 v[32:47], v[112:115], v[80:83], v[32:47]
	ds_read_b128 v[112:115], v204 offset:17344
	s_waitcnt lgkmcnt(7)
	v_mfma_f32_32x32x16_bf16 v[48:63], v[236:239], v[84:87], v[48:63]
	ds_read_b128 v[236:239], v204 offset:480
	s_waitcnt lgkmcnt(7)
	v_mfma_f32_32x32x16_bf16 v[32:47], v[120:123], v[84:87], v[32:47]
	ds_read_b128 v[120:123], v204 offset:17376
	s_waitcnt lgkmcnt(7)
	v_mfma_f32_32x32x16_bf16 v[48:63], v[240:243], v[72:75], v[48:63]
	s_waitcnt lgkmcnt(6)
	v_mfma_f32_32x32x16_bf16 v[32:47], v[244:247], v[72:75], v[32:47]
	s_waitcnt lgkmcnt(5)
	v_mfma_f32_32x32x16_bf16 v[48:63], v[124:127], v[76:79], v[48:63]
	s_waitcnt lgkmcnt(4)
	v_mfma_f32_32x32x16_bf16 v[32:47], v[248:251], v[76:79], v[32:47]
	v_add_u32_e32 v204, 64, v231
	s_waitcnt lgkmcnt(3)
	v_mfma_f32_32x32x16_bf16 v[48:63], v[232:235], v[64:67], v[48:63]
	s_waitcnt lgkmcnt(2)
	v_mfma_f32_32x32x16_bf16 v[32:47], v[112:115], v[64:67], v[32:47]
	s_waitcnt lgkmcnt(1)
	v_mfma_f32_32x32x16_bf16 v[48:63], v[236:239], v[68:71], v[48:63]
	s_waitcnt lgkmcnt(0)
	v_mfma_f32_32x32x16_bf16 v[32:47], v[120:123], v[68:71], v[32:47]
	v_add_u32_e32 v68, v206, v226
	v_or_b32_e32 v64, 0x400, v68
	global_load_dwordx4 v[120:123], v68, s[92:93]
	global_load_dwordx4 v[124:127], v64, s[92:93]
	v_or_b32_e32 v64, 0x800, v68
	global_load_dwordx4 v[112:115], v64, s[92:93]
	v_or_b32_e32 v64, 0xc00, v68
	global_load_dwordx4 v[116:119], v64, s[92:93]
	v_or_b32_e32 v64, 0x1000, v68
	global_load_dwordx4 v[104:107], v64, s[92:93]
	v_or_b32_e32 v64, 0x1400, v68
	global_load_dwordx4 v[108:111], v64, s[92:93]
	v_or_b32_e32 v64, 0x1800, v68
	global_load_dwordx4 v[96:99], v64, s[92:93]
	v_or_b32_e32 v64, 0x1c00, v68
	global_load_dwordx4 v[100:103], v64, s[92:93]
	v_or_b32_e32 v64, 0x2000, v68
	global_load_dwordx4 v[88:91], v64, s[92:93]
	v_or_b32_e32 v64, 0x2400, v68
	global_load_dwordx4 v[92:95], v64, s[92:93]
	v_or_b32_e32 v64, 0x2800, v68
	global_load_dwordx4 v[80:83], v64, s[92:93]
	v_or_b32_e32 v64, 0x2c00, v68
	global_load_dwordx4 v[84:87], v64, s[92:93]
	v_or_b32_e32 v64, 0x3000, v68
	global_load_dwordx4 v[72:75], v64, s[92:93]
	v_or_b32_e32 v64, 0x3400, v68
	v_fmac_f32_e32 v205, v230, v48
	v_and_b32_e32 v48, 0xffff0000, v188
	global_load_dwordx4 v[76:79], v64, s[92:93]
	v_or_b32_e32 v64, 0x3800, v68
	v_or_b32_e32 v68, 0x3c00, v68
	v_fmac_f32_e32 v48, v230, v49
	v_lshlrev_b32_e32 v49, 16, v189
	global_load_dwordx4 v[64:67], v64, s[92:93]
	v_fmac_f32_e32 v49, v230, v50
	global_load_dwordx4 v[68:71], v68, s[92:93]
	v_cvt_pk_bf16_f32 v48, v205, v48
	v_and_b32_e32 v50, 0xffff0000, v189
	v_fmac_f32_e32 v50, v230, v51
	v_cvt_pk_bf16_f32 v49, v49, v50
	global_store_dwordx2 v231, v[48:49], s[18:19]
	s_waitcnt vmcnt(30)
; #define LAS __attribute__((address_space(3)))
; DI unsigned cvt_pk_bf16(float lo, float hi) { unsigned r; asm volatile("v_cvt_pk_bf16_f32 %0, %1, %2" : "=v"(r) : "v"(lo), "v"(hi)); return r; }
; DI float bf_lo(unsigned w) { return __uint_as_float(w << 16); }
; DI float bf_hi(unsigned w) { return __uint_as_float(w & 0xffff0000u); }
; #define MFMA32(a, b, c) __builtin_amdgcn_mfma_f32_32x32x16_bf16((a), (b), (c), 0, 0, 0)
; template <bool XW, int PASS, bool RMW> ...
;     ...
;         for (int gq = 0; gq < 4; ++gq) {
;           u32x2 a; a.x = cvt_pk_bf16(bf_lo(ovn[gq].x) + qe * yc0[4 * gq], bf_hi(ovn[gq].x) + qe * yc0[4 * gq + 1]); a.y = cvt_pk_bf16(bf_lo(ovn[gq].y) + qe * yc0[4 * gq + 2], bf_hi(ovn[gq].y) + qe * yc0[4 * gq + 3]);
;           *(u32x2*)((char*)y + (yb + 16u * gq)) = a;
;           u32x2 c2; c2.x = cvt_pk_bf16(bf_lo(ovn[4 + gq].x) + qe * yc1[4 * gq], bf_hi(ovn[4 + gq].x) + qe * yc1[4 * gq + 1]); c2.y = cvt_pk_bf16(bf_lo(ovn[4 + gq].y) + qe * yc1[4 * gq + 2], bf_hi(ovn[4 + gq].y) + qe * yc1[4 * gq + 3]);
;           *(u32x2*)((char*)y + (yb + 64u + 16u * gq)) = c2;
;         }
;         if constexpr (PASS == 1 && RMW) {
;           const unsigned ybn = yoff0 + (unsigned)cn * 524288u;
; #pragma unroll
;           for (int gq = 0; gq < 8; ++gq) ovn[gq] = *(const u32x2*)((const char*)y + (ybn + 64u * (gq >> 2) + 16u * (gq & 3)));
;         }
;       }
; #pragma unroll
;       for (int i = 0; i < 16; ++i) { st0[i] *= cd; st1[i] *= cd; }
; #pragma unroll
;       for (int sb = 0; sb < 2; ++sb) {
;         bf16x8 a0[4], a1[4];
; #pragma unroll
;         for (int k = 0; k < 4; ++k) { a0[k] = *(const LAS bf16x8*)(vimg + (cc & 1) * 16384 + (4 * sb + k) * 1024 + lane * 16); a1[k] = *(const LAS bf16x8*)(vimg + (cc & 1) * 16384 + 8192 + (4 * sb + k) * 1024 + lane * 16); }
; #pragma unroll
;         for (int k = 0; k < 4; ++k) { st0 = MFMA32(a0[k], kb0[4 * sb + k], st0); st1 = MFMA32(a1[k], kb0[4 * sb + k], st1); }
;         asm volatile("" : "+v"(st0), "+v"(st1) :: "memory");
; #pragma unroll
;         for (int k = 0; k < 4; ++k) kb0[4 * sb + k] = ldg16(kT, kboff0 + (unsigned)cn * 262144u + 1024u * (4 * sb + k));
;       }
	v_lshlrev_b32_e32 v48, 16, v186
	v_fmac_f32_e32 v48, v230, v32
	v_and_b32_e32 v32, 0xffff0000, v186
	v_fmac_f32_e32 v32, v230, v33
	v_lshlrev_b32_e32 v33, 16, v187
	v_fmac_f32_e32 v33, v230, v34
	v_and_b32_e32 v34, 0xffff0000, v187
	v_cvt_pk_bf16_f32 v32, v48, v32
	v_fmac_f32_e32 v34, v230, v35
	v_cvt_pk_bf16_f32 v33, v33, v34
	global_store_dwordx2 v204, v[32:33], s[18:19]
	v_lshlrev_b32_e32 v32, 16, v184
	v_and_b32_e32 v33, 0xffff0000, v184
	v_fmac_f32_e32 v32, v230, v52
	v_fmac_f32_e32 v33, v230, v53
	v_cvt_pk_bf16_f32 v32, v32, v33
	v_lshlrev_b32_e32 v33, 16, v185
	v_and_b32_e32 v34, 0xffff0000, v185
	v_fmac_f32_e32 v33, v230, v54
	v_fmac_f32_e32 v34, v230, v55
	v_cvt_pk_bf16_f32 v33, v33, v34
	v_add_u32_e32 v34, 16, v231
	global_store_dwordx2 v34, v[32:33], s[18:19]
	s_waitcnt vmcnt(31)
	v_lshlrev_b32_e32 v32, 16, v180
	v_and_b32_e32 v33, 0xffff0000, v180
	v_fmac_f32_e32 v32, v230, v36
	v_fmac_f32_e32 v33, v230, v37
	v_cvt_pk_bf16_f32 v32, v32, v33
	v_lshlrev_b32_e32 v33, 16, v181
	v_and_b32_e32 v34, 0xffff0000, v181
	v_fmac_f32_e32 v33, v230, v38
	v_fmac_f32_e32 v34, v230, v39
	v_cvt_pk_bf16_f32 v33, v33, v34
	v_add_u32_e32 v34, 0x50, v231
	global_store_dwordx2 v34, v[32:33], s[18:19]
	v_lshlrev_b32_e32 v32, 16, v178
	v_and_b32_e32 v33, 0xffff0000, v178
	v_fmac_f32_e32 v32, v230, v56
	v_fmac_f32_e32 v33, v230, v57
	v_cvt_pk_bf16_f32 v32, v32, v33
	v_lshlrev_b32_e32 v33, 16, v179
	v_and_b32_e32 v34, 0xffff0000, v179
	v_fmac_f32_e32 v33, v230, v58
	v_fmac_f32_e32 v34, v230, v59
	v_cvt_pk_bf16_f32 v33, v33, v34
	v_add_u32_e32 v34, 32, v231
	global_store_dwordx2 v34, v[32:33], s[18:19]
	s_waitcnt vmcnt(32)
	v_lshlrev_b32_e32 v32, 16, v174
	v_and_b32_e32 v33, 0xffff0000, v174
	v_fmac_f32_e32 v32, v230, v40
	v_fmac_f32_e32 v33, v230, v41
	v_cvt_pk_bf16_f32 v32, v32, v33
	v_lshlrev_b32_e32 v33, 16, v175
	v_and_b32_e32 v34, 0xffff0000, v175
	v_fmac_f32_e32 v33, v230, v42
	v_fmac_f32_e32 v34, v230, v43
	v_cvt_pk_bf16_f32 v33, v33, v34
	v_add_u32_e32 v34, 0x60, v231
	global_store_dwordx2 v34, v[32:33], s[18:19]
	v_lshlrev_b32_e32 v32, 16, v172
	v_and_b32_e32 v33, 0xffff0000, v172
	v_fmac_f32_e32 v32, v230, v60
	v_fmac_f32_e32 v33, v230, v61
	v_cvt_pk_bf16_f32 v32, v32, v33
	v_lshlrev_b32_e32 v33, 16, v173
	v_and_b32_e32 v34, 0xffff0000, v173
	v_fmac_f32_e32 v33, v230, v62
	v_fmac_f32_e32 v34, v230, v63
	v_cvt_pk_bf16_f32 v33, v33, v34
	v_add_u32_e32 v34, 48, v231
	global_store_dwordx2 v34, v[32:33], s[18:19]
	s_waitcnt vmcnt(33)
	v_lshlrev_b32_e32 v32, 16, v170
	v_and_b32_e32 v33, 0xffff0000, v170
	v_fmac_f32_e32 v32, v230, v44
	v_fmac_f32_e32 v33, v230, v45
	v_cvt_pk_bf16_f32 v32, v32, v33
	v_lshlrev_b32_e32 v33, 16, v171
	v_and_b32_e32 v34, 0xffff0000, v171
	v_fmac_f32_e32 v33, v230, v46
	v_fmac_f32_e32 v34, v230, v47
	v_cvt_pk_bf16_f32 v33, v33, v34
	v_add_u32_e32 v34, 0x70, v231
	global_store_dwordx2 v34, v[32:33], s[18:19]
	v_lshl_add_u32 v32, v169, 19, v227
	v_or_b32_e32 v33, 16, v32
	global_load_dwordx2 v[188:189], v32, s[18:19]
	global_load_dwordx2 v[184:185], v33, s[18:19]
	v_or_b32_e32 v33, 32, v32
	global_load_dwordx2 v[178:179], v33, s[18:19]
	v_or_b32_e32 v33, 48, v32
	global_load_dwordx2 v[172:173], v33, s[18:19]
	v_or_b32_e32 v33, 64, v32
	global_load_dwordx2 v[186:187], v33, s[18:19]
	v_or_b32_e32 v33, 0x50, v32
	v_mov_b32_e32 v169, v168
	global_load_dwordx2 v[180:181], v33, s[18:19]
	v_or_b32_e32 v33, 0x60, v32
	v_or_b32_e32 v32, 0x70, v32
	v_pk_mul_f32 v[30:31], v[168:169], v[30:31]
	v_pk_mul_f32 v[28:29], v[168:169], v[28:29]
	v_pk_mul_f32 v[26:27], v[168:169], v[26:27]
	v_pk_mul_f32 v[24:25], v[168:169], v[24:25]
	v_pk_mul_f32 v[22:23], v[168:169], v[22:23]
	v_pk_mul_f32 v[20:21], v[168:169], v[20:21]
	v_pk_mul_f32 v[18:19], v[168:169], v[18:19]
	v_pk_mul_f32 v[14:15], v[168:169], v[14:15]
	v_pk_mul_f32 v[12:13], v[168:169], v[12:13]
	v_pk_mul_f32 v[10:11], v[168:169], v[10:11]
	v_pk_mul_f32 v[8:9], v[168:169], v[8:9]
	v_pk_mul_f32 v[6:7], v[168:169], v[6:7]
	v_pk_mul_f32 v[4:5], v[168:169], v[4:5]
	v_pk_mul_f32 v[2:3], v[168:169], v[2:3]
	v_add_u32_e32 v169, s2, v218
	global_load_dwordx2 v[174:175], v33, s[18:19]
	global_load_dwordx2 v[170:171], v32, s[18:19]
	ds_read_b128 v[32:35], v169
	ds_read_b128 v[36:39], v169 offset:8192
	ds_read_b128 v[40:43], v169 offset:1024
	ds_read_b128 v[44:47], v169 offset:9216
	ds_read_b128 v[48:51], v169 offset:2048
	ds_read_b128 v[52:55], v169 offset:10240
	ds_read_b128 v[56:59], v169 offset:3072
	ds_read_b128 v[60:63], v169 offset:11264
	s_waitcnt vmcnt(41) lgkmcnt(7)
	v_mfma_f32_32x32x16_bf16 v[16:31], v[32:35], v[128:131], v[16:31]
	v_add_u32_e32 v204, v206, v223
	v_or_b32_e32 v32, 0x400, v204
	s_and_b32 s2, s1, 0x4000
	v_add_u32_e32 v231, 0xfff80000, v231
	s_cmp_eq_u32 s4, s8
	s_waitcnt lgkmcnt(6)
	v_mfma_f32_32x32x16_bf16 v[0:15], v[36:39], v[128:131], v[0:15]
	s_waitcnt vmcnt(40) lgkmcnt(5)
	v_mfma_f32_32x32x16_bf16 v[16:31], v[40:43], v[132:135], v[16:31]
	s_waitcnt lgkmcnt(4)
	v_mfma_f32_32x32x16_bf16 v[0:15], v[44:47], v[132:135], v[0:15]
	s_waitcnt vmcnt(39) lgkmcnt(3)
	v_mfma_f32_32x32x16_bf16 v[16:31], v[48:51], v[136:139], v[16:31]
	s_waitcnt lgkmcnt(2)
	v_mfma_f32_32x32x16_bf16 v[0:15], v[52:55], v[136:139], v[0:15]
	s_waitcnt vmcnt(38) lgkmcnt(1)
	v_mfma_f32_32x32x16_bf16 v[16:31], v[56:59], v[140:143], v[16:31]
	s_waitcnt lgkmcnt(0)
	v_mfma_f32_32x32x16_bf16 v[0:15], v[60:63], v[140:143], v[0:15]
	global_load_dwordx4 v[128:131], v204, s[14:15]
	global_load_dwordx4 v[132:135], v32, s[14:15]
	v_or_b32_e32 v32, 0x800, v204
	global_load_dwordx4 v[136:139], v32, s[14:15]
	v_or_b32_e32 v32, 0xc00, v204
	global_load_dwordx4 v[140:143], v32, s[14:15]
	ds_read_b128 v[32:35], v169 offset:4096
	ds_read_b128 v[36:39], v169 offset:12288
	ds_read_b128 v[40:43], v169 offset:5120
	ds_read_b128 v[44:47], v169 offset:13312
	ds_read_b128 v[48:51], v169 offset:6144
	ds_read_b128 v[52:55], v169 offset:14336
	ds_read_b128 v[56:59], v169 offset:7168
	ds_read_b128 v[60:63], v169 offset:15360
	s_waitcnt vmcnt(41) lgkmcnt(7)
; #define LAS __attribute__((address_space(3)))
; DI unsigned cvt_pk_bf16(float lo, float hi) { unsigned r; asm volatile("v_cvt_pk_bf16_f32 %0, %1, %2" : "=v"(r) : "v"(lo), "v"(hi)); return r; }
; #define MFMA32(a, b, c) __builtin_amdgcn_mfma_f32_32x32x16_bf16((a), (b), (c), 0, 0, 0)
; template <bool XW, int PASS, bool RMW> ...
;     ...
;       for (int sb = 0; sb < 2; ++sb) {
;         bf16x8 a0[4], a1[4];
; #pragma unroll
;         for (int k = 0; k < 4; ++k) { a0[k] = *(const LAS bf16x8*)(vimg + (cc & 1) * 16384 + (4 * sb + k) * 1024 + lane * 16); a1[k] = *(const LAS bf16x8*)(vimg + (cc & 1) * 16384 + 8192 + (4 * sb + k) * 1024 + lane * 16); }
; #pragma unroll
;         for (int k = 0; k < 4; ++k) { st0 = MFMA32(a0[k], kb0[4 * sb + k], st0); st1 = MFMA32(a1[k], kb0[4 * sb + k], st1); }
;         asm volatile("" : "+v"(st0), "+v"(st1) :: "memory");
; #pragma unroll
;         for (int k = 0; k < 4; ++k) kb0[4 * sb + k] = ldg16(kT, kboff0 + (unsigned)cn * 262144u + 1024u * (4 * sb + k));
;       }
; #pragma unroll
;       for (int t = 0; t < 2; ++t) {
;         const int sv = 2 * dq + t;
;         *(LAS bf16x8*)(vimg + ((cc + 1) & 1) * 16384 + et * 8192 + sv * 1024 + lane * 16) = scale_tab(vr[t], kdec + 16 * sv + 8 * h);
;         vr[t] = ldg16(vT, vaoff0 + (unsigned)cnn * 524288u + 1024u * sv);
;       }
;       LAS bf16_t* sw = Sb + (pbuf ^ 1) * SBE + (4 * h) * 264 + 32 * w + r;
; #pragma unroll
;       for (int i = 0; i < 16; ++i) {
;         const int eo = ((i & 3) + 8 * (i >> 2)) * 264;
;         const unsigned pkw = cvt_pk_bf16(st0[i], st1[i]);
;         sw[eo] = (bf16_t)(pkw & 0xffffu);
;         sw[eo + 32 * 264] = (bf16_t)(pkw >> 16);
;       }
;       lds_barrier();
;       pbuf ^= 1;
	v_mfma_f32_32x32x16_bf16 v[16:31], v[32:35], v[144:147], v[16:31]
	v_or_b32_e32 v32, 0x1000, v204
	s_waitcnt lgkmcnt(6)
	v_mfma_f32_32x32x16_bf16 v[0:15], v[36:39], v[144:147], v[0:15]
	s_waitcnt vmcnt(40) lgkmcnt(5)
	v_mfma_f32_32x32x16_bf16 v[16:31], v[40:43], v[148:151], v[16:31]
	s_waitcnt vmcnt(37)
	v_lshlrev_b32_e32 v42, 16, v160
	v_add_u32_e32 v40, s2, v198
	v_lshl_add_u32 v41, v203, 19, v224
	s_mul_i32 s2, s0, 0x8400
	s_waitcnt lgkmcnt(4)
	v_mfma_f32_32x32x16_bf16 v[0:15], v[44:47], v[148:151], v[0:15]
	s_waitcnt lgkmcnt(3)
	v_mfma_f32_32x32x16_bf16 v[16:31], v[48:51], v[152:155], v[16:31]
	s_waitcnt lgkmcnt(2)
	v_mfma_f32_32x32x16_bf16 v[0:15], v[52:55], v[152:155], v[0:15]
	s_waitcnt lgkmcnt(1)
	v_mfma_f32_32x32x16_bf16 v[16:31], v[56:59], v[156:159], v[16:31]
	s_waitcnt lgkmcnt(0)
	v_mfma_f32_32x32x16_bf16 v[0:15], v[60:63], v[156:159], v[0:15]
	global_load_dwordx4 v[144:147], v32, s[14:15]
	v_or_b32_e32 v32, 0x1400, v204
	global_load_dwordx4 v[148:151], v32, s[14:15]
	v_or_b32_e32 v32, 0x1800, v204
	global_load_dwordx4 v[152:155], v32, s[14:15]
	v_or_b32_e32 v32, 0x1c00, v204
	global_load_dwordx4 v[156:159], v32, s[14:15]
	ds_read_b128 v[32:35], v228
	ds_read_b128 v[36:39], v228 offset:16
	s_waitcnt lgkmcnt(1)
	v_mul_f32_e32 v32, v32, v42
	v_and_b32_e32 v42, 0xffff0000, v160
	v_mul_f32_e32 v33, v33, v42
	v_cvt_pk_bf16_f32 v32, v32, v33
	v_lshlrev_b32_e32 v33, 16, v161
	v_mul_f32_e32 v33, v34, v33
	v_and_b32_e32 v34, 0xffff0000, v161
	v_mul_f32_e32 v34, v35, v34
	v_cvt_pk_bf16_f32 v33, v33, v34
	v_lshlrev_b32_e32 v34, 16, v162
	v_and_b32_e32 v35, 0xffff0000, v162
	s_waitcnt lgkmcnt(0)
	v_mul_f32_e32 v34, v36, v34
	v_mul_f32_e32 v35, v37, v35
	v_cvt_pk_bf16_f32 v34, v34, v35
	v_lshlrev_b32_e32 v35, 16, v163
	v_and_b32_e32 v36, 0xffff0000, v163
	v_mul_f32_e32 v35, v38, v35
	v_mul_f32_e32 v36, v39, v36
	v_cvt_pk_bf16_f32 v35, v35, v36
	v_add_u32_e32 v36, s3, v40
	ds_write_b128 v36, v[32:35]
	v_or_b32_e32 v32, s3, v41
	global_load_dwordx4 v[160:163], v32, s[16:17]
	ds_read_b128 v[32:35], v229
	ds_read_b128 v[36:39], v229 offset:16
	s_waitcnt vmcnt(41)
	v_lshlrev_b32_e32 v42, 16, v164
	s_waitcnt lgkmcnt(1)
	v_mul_f32_e32 v32, v32, v42
	v_and_b32_e32 v42, 0xffff0000, v164
	v_mul_f32_e32 v33, v33, v42
	v_cvt_pk_bf16_f32 v32, v32, v33
	v_lshlrev_b32_e32 v33, 16, v165
	v_mul_f32_e32 v33, v34, v33
	v_and_b32_e32 v34, 0xffff0000, v165
	v_mul_f32_e32 v34, v35, v34
	v_cvt_pk_bf16_f32 v33, v33, v34
	v_lshlrev_b32_e32 v34, 16, v166
	v_and_b32_e32 v35, 0xffff0000, v166
	s_waitcnt lgkmcnt(0)
	v_mul_f32_e32 v34, v36, v34
	v_mul_f32_e32 v35, v37, v35
	v_cvt_pk_bf16_f32 v34, v34, v35
	v_lshlrev_b32_e32 v35, 16, v167
	v_and_b32_e32 v36, 0xffff0000, v167
	v_mul_f32_e32 v35, v38, v35
	v_mul_f32_e32 v36, v39, v36
	v_cvt_pk_bf16_f32 v35, v35, v36
	v_add_u32_e32 v36, s33, v40
	ds_write_b128 v36, v[32:35]
	v_or_b32_e32 v32, s33, v41
	global_load_dwordx4 v[164:167], v32, s[16:17]
	v_add_u32_e32 v32, s2, v199
	v_mbcnt_lo_u32_b32 v251, -1, 0
	v_mbcnt_hi_u32_b32 v251, -1, v251
	v_and_b32_e32 v251, 1, v251
	v_sub_u32_e32 v250, 0, v251
	v_and_b32_e32 v248, 0x06060606, v250
	v_xor_b32_e32 v248, 0x05040100, v248
	v_and_b32_e32 v251, 0x107e, v250
	v_add_u32_e32 v249, v32, v251
	v_cvt_pk_bf16_f32 v232, v16, v20
	v_cvt_pk_bf16_f32 v233, v17, v21
	v_cvt_pk_bf16_f32 v234, v18, v22
	v_cvt_pk_bf16_f32 v235, v19, v23
	v_cvt_pk_bf16_f32 v236, v24, v28
	v_cvt_pk_bf16_f32 v237, v25, v29
	v_cvt_pk_bf16_f32 v238, v26, v30
	v_cvt_pk_bf16_f32 v239, v27, v31
	v_mov_b32_dpp v240, v232 quad_perm:[1,0,3,2] row_mask:0xf bank_mask:0xf
	v_mov_b32_dpp v241, v233 quad_perm:[1,0,3,2] row_mask:0xf bank_mask:0xf
	v_mov_b32_dpp v242, v234 quad_perm:[1,0,3,2] row_mask:0xf bank_mask:0xf
	v_mov_b32_dpp v243, v235 quad_perm:[1,0,3,2] row_mask:0xf bank_mask:0xf
	v_mov_b32_dpp v244, v236 quad_perm:[1,0,3,2] row_mask:0xf bank_mask:0xf
	v_mov_b32_dpp v245, v237 quad_perm:[1,0,3,2] row_mask:0xf bank_mask:0xf
	v_mov_b32_dpp v246, v238 quad_perm:[1,0,3,2] row_mask:0xf bank_mask:0xf
	v_mov_b32_dpp v247, v239 quad_perm:[1,0,3,2] row_mask:0xf bank_mask:0xf
	v_perm_b32 v240, v240, v232, v248
	v_perm_b32 v241, v241, v233, v248
	v_perm_b32 v242, v242, v234, v248
	v_perm_b32 v243, v243, v235, v248
	v_perm_b32 v244, v244, v236, v248
	v_perm_b32 v245, v245, v237, v248
	v_perm_b32 v246, v246, v238, v248
	v_perm_b32 v247, v247, v239, v248
	ds_write_b32 v249, v240 offset:0
	ds_write_b32 v249, v241 offset:528
	ds_write_b32 v249, v242 offset:1056
	ds_write_b32 v249, v243 offset:1584
	ds_write_b32 v249, v244 offset:8448
	ds_write_b32 v249, v245 offset:8976
	ds_write_b32 v249, v246 offset:9504
	ds_write_b32 v249, v247 offset:10032
	v_cvt_pk_bf16_f32 v232, v0, v4
	v_cvt_pk_bf16_f32 v233, v1, v5
	v_cvt_pk_bf16_f32 v234, v2, v6
	v_cvt_pk_bf16_f32 v235, v3, v7
	v_cvt_pk_bf16_f32 v236, v8, v12
	v_cvt_pk_bf16_f32 v237, v9, v13
	v_cvt_pk_bf16_f32 v238, v10, v14
	v_cvt_pk_bf16_f32 v239, v11, v15
	v_mov_b32_dpp v240, v232 quad_perm:[1,0,3,2] row_mask:0xf bank_mask:0xf
	v_mov_b32_dpp v241, v233 quad_perm:[1,0,3,2] row_mask:0xf bank_mask:0xf
	v_mov_b32_dpp v242, v234 quad_perm:[1,0,3,2] row_mask:0xf bank_mask:0xf
	v_mov_b32_dpp v243, v235 quad_perm:[1,0,3,2] row_mask:0xf bank_mask:0xf
	v_mov_b32_dpp v244, v236 quad_perm:[1,0,3,2] row_mask:0xf bank_mask:0xf
	v_mov_b32_dpp v245, v237 quad_perm:[1,0,3,2] row_mask:0xf bank_mask:0xf
	v_mov_b32_dpp v246, v238 quad_perm:[1,0,3,2] row_mask:0xf bank_mask:0xf
	v_mov_b32_dpp v247, v239 quad_perm:[1,0,3,2] row_mask:0xf bank_mask:0xf
	v_perm_b32 v240, v240, v232, v248
	v_perm_b32 v241, v241, v233, v248
	v_perm_b32 v242, v242, v234, v248
	v_perm_b32 v243, v243, v235, v248
	v_perm_b32 v244, v244, v236, v248
	v_perm_b32 v245, v245, v237, v248
	v_perm_b32 v246, v246, v238, v248
	v_perm_b32 v247, v247, v239, v248
	ds_write_b32 v249, v240 offset:16896
	ds_write_b32 v249, v241 offset:17424
	ds_write_b32 v249, v242 offset:17952
	ds_write_b32 v249, v243 offset:18480
	ds_write_b32 v249, v244 offset:25344
	ds_write_b32 v249, v245 offset:25872
	ds_write_b32 v249, v246 offset:26400
	ds_write_b32 v249, v247 offset:26928
	s_waitcnt lgkmcnt(0)
	s_barrier
	s_mov_b32 s2, s8
	s_cbranch_scc0 .LBB0_102

; #define LAS __attribute__((address_space(3)))
; #define MFMA32(a, b, c) __builtin_amdgcn_mfma_f32_32x32x16_bf16((a), (b), (c), 0, 0, 0)
; template <bool XW, int PASS, bool RMW> ...
;     ...
;       if constexpr (XW) {
;         const unsigned yb = yoff0 + (unsigned)c * 524288u;
;         f32x16 yc0, yc1;
; #pragma unroll
;         for (int i = 0; i < 16; ++i) { yc0[i] = 0.f; yc1[i] = 0.f; }
;         const LAS bf16_t* sp = Sb + pbuf * SBE + r * 264 + 8 * h;
; #pragma unroll
;         for (int sb = 0; sb < 8; ++sb) {
;           bf16x8 a0[2], a1[2];
; #pragma unroll
;           for (int k = 0; k < 2; ++k) { a0[k] = *(const LAS bf16x8*)(sp + 16 * (2 * sb + k)); a1[k] = *(const LAS bf16x8*)(sp + 32 * 264 + 16 * (2 * sb + k)); }
; #pragma unroll
;           for (int k = 0; k < 2; ++k) { yc0 = MFMA32(a0[k], qf[2 * sb + k], yc0); yc1 = MFMA32(a1[k], qf[2 * sb + k], yc1); }
;         }
;         asm volatile("" : "+v"(yc0), "+v"(yc1) :: "memory");
; #pragma unroll
;         for (int s = 0; s < 16; ++s) qf[s] = ldg16(qr, qoff0 + (unsigned)cn * 262144u + 1024u * s);
.LBB0_108:
	s_mul_i32 s2, s0, 0x8400
	v_add_u32_e32 v186, s2, v217
	ds_read_b128 v[228:231], v186
	ds_read_b128 v[232:235], v186 offset:16896
	ds_read_b128 v[236:239], v186 offset:32
	ds_read_b128 v[240:243], v186 offset:16928
	ds_read_b128 v[244:247], v186 offset:64
	ds_read_b128 v[248:251], v186 offset:16960
	s_add_i32 s2, s8, 1
	v_mov_b32_e32 v169, v168
	s_and_b32 s9, s1, 0x4000
	s_waitcnt vmcnt(33)
	s_waitcnt lgkmcnt(5)
	v_mfma_f32_32x32x16_bf16 v[48:63], v[228:231], v[124:127], 0
	ds_read_b128 v[228:231], v186 offset:96
	v_mul_f32_e64 v30, v168, v30
	v_mul_f32_e64 v31, v169, v31
	v_mul_f32_e64 v28, v168, v28
	v_mul_f32_e64 v29, v169, v29
	v_pk_mul_f32 v[26:27], v[168:169], v[26:27]
	v_pk_mul_f32 v[24:25], v[168:169], v[24:25]
	v_pk_mul_f32 v[22:23], v[168:169], v[22:23]
	v_pk_mul_f32 v[20:21], v[168:169], v[20:21]
	s_waitcnt lgkmcnt(5)
	v_mfma_f32_32x32x16_bf16 v[32:47], v[232:235], v[124:127], 0
	ds_read_b128 v[232:235], v186 offset:16992
	ds_read_b128 v[124:127], v186 offset:128
	v_mul_f32_e64 v18, v168, v18
	v_mul_f32_e64 v19, v169, v19
	v_mul_f32_e64 v14, v168, v14
	v_mul_f32_e64 v15, v169, v15
	v_mul_f32_e64 v12, v168, v12
	v_mul_f32_e64 v13, v169, v13
	v_pk_mul_f32 v[10:11], v[168:169], v[10:11]
	v_pk_mul_f32 v[8:9], v[168:169], v[8:9]
	v_pk_mul_f32 v[6:7], v[168:169], v[6:7]
	v_pk_mul_f32 v[4:5], v[168:169], v[4:5]
	s_waitcnt vmcnt(32)
	s_waitcnt lgkmcnt(6)
	v_mfma_f32_32x32x16_bf16 v[48:63], v[236:239], v[120:123], v[48:63]
	ds_read_b128 v[236:239], v186 offset:17024
	v_mul_f32_e64 v2, v168, v2
	v_mul_f32_e64 v3, v169, v3
	v_add_u32_e32 v169, s9, v218
	v_mul_f32_e64 v16, v170, v16
	v_mul_f32_e64 v17, v171, v17
	v_pk_mul_f32 v[0:1], v[170:171], v[0:1]
	s_add_i32 s8, s8, 2
	s_addk_i32 s1, 0x4000
	s_xor_b32 s0, s0, 1
	s_waitcnt lgkmcnt(6)
	v_mfma_f32_32x32x16_bf16 v[32:47], v[240:243], v[120:123], v[32:47]
	ds_read_b128 v[240:243], v186 offset:160
	ds_read_b128 v[120:123], v186 offset:17056
	v_add_u32_e32 v182, 0x60, v175
	v_add_u32_e32 v183, 48, v175
	s_waitcnt vmcnt(31)
	s_waitcnt lgkmcnt(7)
	v_mfma_f32_32x32x16_bf16 v[48:63], v[244:247], v[116:119], v[48:63]
	ds_read_b128 v[244:247], v186 offset:192
	s_waitcnt lgkmcnt(7)
	v_mfma_f32_32x32x16_bf16 v[32:47], v[248:251], v[116:119], v[32:47]
	ds_read_b128 v[248:251], v186 offset:17088
	s_waitcnt vmcnt(30)
	s_waitcnt lgkmcnt(7)
	v_mfma_f32_32x32x16_bf16 v[48:63], v[228:231], v[112:115], v[48:63]
	ds_read_b128 v[228:231], v186 offset:224
	s_waitcnt lgkmcnt(7)
	v_mfma_f32_32x32x16_bf16 v[32:47], v[232:235], v[112:115], v[32:47]
	ds_read_b128 v[232:235], v186 offset:17120
	v_add_u32_e32 v178, 64, v175
	v_add_u32_e32 v179, 16, v175
	v_add_u32_e32 v180, 0x50, v175
	v_add_u32_e32 v181, 32, v175
	s_waitcnt vmcnt(29)
	s_waitcnt lgkmcnt(7)
	v_mfma_f32_32x32x16_bf16 v[48:63], v[124:127], v[108:111], v[48:63]
	ds_read_b128 v[124:127], v186 offset:256
	s_waitcnt lgkmcnt(7)
	v_mfma_f32_32x32x16_bf16 v[32:47], v[236:239], v[108:111], v[32:47]
	ds_read_b128 v[236:239], v186 offset:17152
	s_waitcnt vmcnt(28)
	s_waitcnt lgkmcnt(7)
	v_mfma_f32_32x32x16_bf16 v[48:63], v[240:243], v[104:107], v[48:63]
	ds_read_b128 v[240:243], v186 offset:288
	s_waitcnt lgkmcnt(7)
	v_mfma_f32_32x32x16_bf16 v[32:47], v[120:123], v[104:107], v[32:47]
	ds_read_b128 v[120:123], v186 offset:17184
	s_waitcnt vmcnt(27)
	s_waitcnt lgkmcnt(7)
	v_mfma_f32_32x32x16_bf16 v[48:63], v[244:247], v[100:103], v[48:63]
	ds_read_b128 v[244:247], v186 offset:320
	s_waitcnt lgkmcnt(7)
	v_mfma_f32_32x32x16_bf16 v[32:47], v[248:251], v[100:103], v[32:47]
	ds_read_b128 v[248:251], v186 offset:17216
	s_waitcnt vmcnt(26)
	s_waitcnt lgkmcnt(7)
	v_mfma_f32_32x32x16_bf16 v[48:63], v[228:231], v[96:99], v[48:63]
	ds_read_b128 v[228:231], v186 offset:352
	s_waitcnt lgkmcnt(7)
	v_mfma_f32_32x32x16_bf16 v[32:47], v[232:235], v[96:99], v[32:47]
	ds_read_b128 v[232:235], v186 offset:17248
	s_waitcnt vmcnt(25)
	s_waitcnt lgkmcnt(7)
	v_mfma_f32_32x32x16_bf16 v[48:63], v[124:127], v[92:95], v[48:63]
	ds_read_b128 v[124:127], v186 offset:384
	s_waitcnt lgkmcnt(7)
	v_mfma_f32_32x32x16_bf16 v[32:47], v[236:239], v[92:95], v[32:47]
	ds_read_b128 v[236:239], v186 offset:17280
	s_waitcnt vmcnt(24)
	s_waitcnt lgkmcnt(7)
	v_mfma_f32_32x32x16_bf16 v[48:63], v[240:243], v[88:91], v[48:63]
	ds_read_b128 v[240:243], v186 offset:416
	s_waitcnt lgkmcnt(7)
	v_mfma_f32_32x32x16_bf16 v[32:47], v[120:123], v[88:91], v[32:47]
	ds_read_b128 v[120:123], v186 offset:17312
	s_waitcnt vmcnt(23)
	s_waitcnt lgkmcnt(7)
	v_mfma_f32_32x32x16_bf16 v[48:63], v[244:247], v[84:87], v[48:63]
	ds_read_b128 v[244:247], v186 offset:448
	s_waitcnt lgkmcnt(7)
	v_mfma_f32_32x32x16_bf16 v[32:47], v[248:251], v[84:87], v[32:47]
	ds_read_b128 v[248:251], v186 offset:17344
	s_waitcnt vmcnt(22)
	s_waitcnt lgkmcnt(7)
	v_mfma_f32_32x32x16_bf16 v[48:63], v[228:231], v[80:83], v[48:63]
	ds_read_b128 v[228:231], v186 offset:480
	v_mov_b32_e32 v92, s2
	s_waitcnt lgkmcnt(7)
	v_mfma_f32_32x32x16_bf16 v[32:47], v[232:235], v[80:83], v[32:47]
	ds_read_b128 v[232:235], v186 offset:17376
	s_waitcnt vmcnt(21)
	s_waitcnt lgkmcnt(7)
	v_mfma_f32_32x32x16_bf16 v[48:63], v[124:127], v[76:79], v[48:63]
	s_waitcnt lgkmcnt(6)
	v_mfma_f32_32x32x16_bf16 v[32:47], v[236:239], v[76:79], v[32:47]
	s_waitcnt vmcnt(20)
	s_waitcnt lgkmcnt(5)
	v_mfma_f32_32x32x16_bf16 v[48:63], v[240:243], v[72:75], v[48:63]
	v_sub_u32_e64 v84, s5, v92 clamp
	v_lshlrev_b32_e32 v184, 18, v84
	v_add_u32_e32 v84, v184, v226
	v_or_b32_e32 v85, 0x400, v84
	v_or_b32_e32 v185, 0x3400, v84
	v_or_b32_e32 v187, 0x3c00, v84
	s_waitcnt lgkmcnt(4)
	v_mfma_f32_32x32x16_bf16 v[32:47], v[120:123], v[72:75], v[32:47]
	s_waitcnt vmcnt(19)
	s_waitcnt lgkmcnt(3)
; #define LAS __attribute__((address_space(3)))
; DI unsigned cvt_pk_bf16(float lo, float hi) { unsigned r; asm volatile("v_cvt_pk_bf16_f32 %0, %1, %2" : "=v"(r) : "v"(lo), "v"(hi)); return r; }
; DI float bf_lo(unsigned w) { return __uint_as_float(w << 16); }
; DI float bf_hi(unsigned w) { return __uint_as_float(w & 0xffff0000u); }
; #define MFMA32(a, b, c) __builtin_amdgcn_mfma_f32_32x32x16_bf16((a), (b), (c), 0, 0, 0)
; template <bool XW, int PASS, bool RMW> ...
;     ...
;         for (int s = 0; s < 16; ++s) qf[s] = ldg16(qr, qoff0 + (unsigned)cn * 262144u + 1024u * s);
;         const float qe = cc > 0 ? qd : 0.f;
; #pragma unroll
;         for (int gq = 0; gq < 4; ++gq) {
;           u32x2 a; a.x = cvt_pk_bf16(bf_lo(ovn[gq].x) + qe * yc0[4 * gq], bf_hi(ovn[gq].x) + qe * yc0[4 * gq + 1]); a.y = cvt_pk_bf16(bf_lo(ovn[gq].y) + qe * yc0[4 * gq + 2], bf_hi(ovn[gq].y) + qe * yc0[4 * gq + 3]);
;           *(u32x2*)((char*)y + (yb + 16u * gq)) = a;
;           u32x2 c2; c2.x = cvt_pk_bf16(bf_lo(ovn[4 + gq].x) + qe * yc1[4 * gq], bf_hi(ovn[4 + gq].x) + qe * yc1[4 * gq + 1]); c2.y = cvt_pk_bf16(bf_lo(ovn[4 + gq].y) + qe * yc1[4 * gq + 2], bf_hi(ovn[4 + gq].y) + qe * yc1[4 * gq + 3]);
;           *(u32x2*)((char*)y + (yb + 64u + 16u * gq)) = c2;
;         }
;         if constexpr (PASS == 1 && RMW) {
;           const unsigned ybn = yoff0 + (unsigned)cn * 524288u;
; #pragma unroll
;           for (int gq = 0; gq < 8; ++gq) ovn[gq] = *(const u32x2*)((const char*)y + (ybn + 64u * (gq >> 2) + 16u * (gq & 3)));
;         }
;       }
; #pragma unroll
;       for (int i = 0; i < 16; ++i) { st0[i] *= cd; st1[i] *= cd; }
; #pragma unroll
;       for (int sb = 0; sb < 2; ++sb) {
;         bf16x8 a0[4], a1[4];
; #pragma unroll
;         for (int k = 0; k < 4; ++k) { a0[k] = *(const LAS bf16x8*)(vimg + (cc & 1) * 16384 + (4 * sb + k) * 1024 + lane * 16); a1[k] = *(const LAS bf16x8*)(vimg + (cc & 1) * 16384 + 8192 + (4 * sb + k) * 1024 + lane * 16); }
; #pragma unroll
;         for (int k = 0; k < 4; ++k) { st0 = MFMA32(a0[k], kb0[4 * sb + k], st0); st1 = MFMA32(a1[k], kb0[4 * sb + k], st1); }
;         asm volatile("" : "+v"(st0), "+v"(st1) :: "memory");
; #pragma unroll
;         for (int k = 0; k < 4; ++k) kb0[4 * sb + k] = ldg16(kT, kboff0 + (unsigned)cn * 262144u + 1024u * (4 * sb + k));
	v_mfma_f32_32x32x16_bf16 v[48:63], v[244:247], v[68:71], v[48:63]
	v_or_b32_e32 v186, 0x3800, v84
	s_waitcnt lgkmcnt(2)
	v_mfma_f32_32x32x16_bf16 v[32:47], v[248:251], v[68:71], v[32:47]
	v_or_b32_e32 v68, 0x800, v84
	v_or_b32_e32 v69, 0xc00, v84
	v_or_b32_e32 v70, 0x1000, v84
	v_or_b32_e32 v71, 0x1400, v84
	v_or_b32_e32 v72, 0x1800, v84
	v_or_b32_e32 v73, 0x1c00, v84
	v_or_b32_e32 v74, 0x2000, v84
	s_waitcnt vmcnt(18)
	s_waitcnt lgkmcnt(1)
	v_mfma_f32_32x32x16_bf16 v[48:63], v[228:231], v[64:67], v[48:63]
	v_or_b32_e32 v75, 0x2400, v84
	v_or_b32_e32 v76, 0x2800, v84
	v_or_b32_e32 v77, 0x2c00, v84
	v_or_b32_e32 v78, 0x3000, v84
	s_waitcnt lgkmcnt(0)
	v_mfma_f32_32x32x16_bf16 v[32:47], v[232:235], v[64:67], v[32:47]
	global_load_dwordx4 v[124:127], v84, s[92:93]
	global_load_dwordx4 v[120:123], v85, s[92:93]
	global_load_dwordx4 v[116:119], v68, s[92:93]
	global_load_dwordx4 v[112:115], v69, s[92:93]
	global_load_dwordx4 v[108:111], v70, s[92:93]
	global_load_dwordx4 v[104:107], v71, s[92:93]
	global_load_dwordx4 v[100:103], v72, s[92:93]
	global_load_dwordx4 v[96:99], v73, s[92:93]
	global_load_dwordx4 v[92:95], v74, s[92:93]
	global_load_dwordx4 v[88:91], v75, s[92:93]
	global_load_dwordx4 v[84:87], v76, s[92:93]
	global_load_dwordx4 v[80:83], v77, s[92:93]
	s_nop 0
	global_load_dwordx4 v[76:79], v78, s[92:93]
	s_nop 0
	global_load_dwordx4 v[72:75], v185, s[92:93]
	global_load_dwordx4 v[68:71], v186, s[92:93]
	global_load_dwordx4 v[64:67], v187, s[92:93]
	v_fma_f32 v48, v174, v48, 0
	v_fma_f32 v49, v174, v49, 0
	v_fma_f32 v50, v174, v50, 0
	v_fma_f32 v51, v174, v51, 0
	v_fma_f32 v185, v174, v32, 0
	v_fma_f32 v186, v174, v33, 0
	v_cvt_pk_bf16_f32 v32, v48, v49
	v_cvt_pk_bf16_f32 v33, v50, v51
	v_fma_f32 v34, v174, v34, 0
	v_fma_f32 v35, v174, v35, 0
	global_store_dwordx2 v175, v[32:33], s[10:11]
	v_cvt_pk_bf16_f32 v32, v185, v186
	v_cvt_pk_bf16_f32 v33, v34, v35
	v_fma_f32 v52, v174, v52, 0
	v_fma_f32 v53, v174, v53, 0
	v_fma_f32 v54, v174, v54, 0
	v_fma_f32 v55, v174, v55, 0
	global_store_dwordx2 v178, v[32:33], s[10:11]
	v_cvt_pk_bf16_f32 v32, v52, v53
	v_cvt_pk_bf16_f32 v33, v54, v55
	v_fma_f32 v36, v174, v36, 0
	v_fma_f32 v37, v174, v37, 0
	v_fma_f32 v38, v174, v38, 0
	v_fma_f32 v39, v174, v39, 0
	global_store_dwordx2 v179, v[32:33], s[10:11]
	v_cvt_pk_bf16_f32 v32, v36, v37
	v_cvt_pk_bf16_f32 v33, v38, v39
	v_fma_f32 v56, v174, v56, 0
	v_fma_f32 v57, v174, v57, 0
	v_fma_f32 v58, v174, v58, 0
	v_fma_f32 v59, v174, v59, 0
	global_store_dwordx2 v180, v[32:33], s[10:11]
	v_cvt_pk_bf16_f32 v32, v56, v57
	v_cvt_pk_bf16_f32 v33, v58, v59
	v_fma_f32 v40, v174, v40, 0
	v_fma_f32 v41, v174, v41, 0
	v_fma_f32 v42, v174, v42, 0
	v_fma_f32 v43, v174, v43, 0
	global_store_dwordx2 v181, v[32:33], s[10:11]
	v_cvt_pk_bf16_f32 v32, v40, v41
	v_cvt_pk_bf16_f32 v33, v42, v43
	v_fma_f32 v60, v174, v60, 0
	v_fma_f32 v61, v174, v61, 0
	v_fma_f32 v62, v174, v62, 0
	v_fma_f32 v63, v174, v63, 0
	v_fma_f32 v44, v174, v44, 0
	v_fma_f32 v45, v174, v45, 0
	global_store_dwordx2 v182, v[32:33], s[10:11]
	v_cvt_pk_bf16_f32 v32, v60, v61
	v_cvt_pk_bf16_f32 v33, v62, v63
	v_fma_f32 v46, v174, v46, 0
	v_fma_f32 v47, v174, v47, 0
	global_store_dwordx2 v183, v[32:33], s[10:11]
	v_cvt_pk_bf16_f32 v44, v44, v45
	v_cvt_pk_bf16_f32 v45, v46, v47
	ds_read_b128 v[228:231], v169
	ds_read_b128 v[232:235], v169 offset:8192
	ds_read_b128 v[236:239], v169 offset:1024
	ds_read_b128 v[240:243], v169 offset:9216
	ds_read_b128 v[244:247], v169 offset:2048
	ds_read_b128 v[248:251], v169 offset:10240
	s_waitcnt vmcnt(32)
	s_waitcnt lgkmcnt(5)
	v_mfma_f32_32x32x16_bf16 v[16:31], v[228:231], v[164:167], v[16:31]
	ds_read_b128 v[228:231], v169 offset:3072
	s_waitcnt vmcnt(24)
	v_lshlrev_b32_e32 v46, 16, v152
	v_and_b32_e32 v47, 0xffff0000, v152
	v_lshlrev_b32_e32 v48, 16, v153
	v_and_b32_e32 v49, 0xffff0000, v153
	v_lshlrev_b32_e32 v50, 16, v154
	v_and_b32_e32 v51, 0xffff0000, v154
	s_waitcnt lgkmcnt(5)
	v_mfma_f32_32x32x16_bf16 v[0:15], v[232:235], v[164:167], v[0:15]
	ds_read_b128 v[232:235], v169 offset:11264
	v_lshlrev_b32_e32 v52, 16, v155
	v_and_b32_e32 v53, 0xffff0000, v155
	s_waitcnt vmcnt(23)
	v_lshlrev_b32_e32 v54, 16, v149
	v_and_b32_e32 v55, 0xffff0000, v149
	v_lshlrev_b32_e32 v56, 16, v150
	v_and_b32_e32 v57, 0xffff0000, v150
	v_lshlrev_b32_e32 v58, 16, v151
	s_waitcnt lgkmcnt(5)
	v_mfma_f32_32x32x16_bf16 v[16:31], v[236:239], v[160:163], v[16:31]
	ds_read_b128 v[236:239], v169 offset:4096
	v_and_b32_e32 v59, 0xffff0000, v151
	s_waitcnt lgkmcnt(5)
	v_mfma_f32_32x32x16_bf16 v[0:15], v[240:243], v[160:163], v[0:15]
	ds_read_b128 v[240:243], v169 offset:12288
	s_waitcnt lgkmcnt(5)
	v_mfma_f32_32x32x16_bf16 v[16:31], v[244:247], v[156:159], v[16:31]
	ds_read_b128 v[244:247], v169 offset:5120
	s_waitcnt lgkmcnt(5)
	v_mfma_f32_32x32x16_bf16 v[0:15], v[248:251], v[156:159], v[0:15]
	ds_read_b128 v[248:251], v169 offset:13312
	v_add_u32_e32 v32, 0x70, v175
	global_store_dwordx2 v32, v[44:45], s[10:11]
	v_lshlrev_b32_e32 v44, 16, v148
	v_and_b32_e32 v45, 0xffff0000, v148
	v_add_u32_e32 v175, 0xfff80000, v175
	s_waitcnt lgkmcnt(5)
	v_mfma_f32_32x32x16_bf16 v[16:31], v[228:231], v[140:143], v[16:31]
	ds_read_b128 v[228:231], v169 offset:6144
	s_waitcnt lgkmcnt(5)
	v_mfma_f32_32x32x16_bf16 v[0:15], v[232:235], v[140:143], v[0:15]
	ds_read_b128 v[232:235], v169 offset:14336
	s_waitcnt lgkmcnt(5)
	v_mfma_f32_32x32x16_bf16 v[16:31], v[236:239], v[144:147], v[16:31]
	ds_read_b128 v[236:239], v169 offset:7168
	s_waitcnt lgkmcnt(5)
; #define LAS __attribute__((address_space(3)))
; DI unsigned cvt_pk_bf16(float lo, float hi) { unsigned r; asm volatile("v_cvt_pk_bf16_f32 %0, %1, %2" : "=v"(r) : "v"(lo), "v"(hi)); return r; }
; #define MFMA32(a, b, c) __builtin_amdgcn_mfma_f32_32x32x16_bf16((a), (b), (c), 0, 0, 0)
; template <bool XW, int PASS, bool RMW> ...
;     ...
;       for (int sb = 0; sb < 2; ++sb) {
;         bf16x8 a0[4], a1[4];
; #pragma unroll
;         for (int k = 0; k < 4; ++k) { a0[k] = *(const LAS bf16x8*)(vimg + (cc & 1) * 16384 + (4 * sb + k) * 1024 + lane * 16); a1[k] = *(const LAS bf16x8*)(vimg + (cc & 1) * 16384 + 8192 + (4 * sb + k) * 1024 + lane * 16); }
; #pragma unroll
;         for (int k = 0; k < 4; ++k) { st0 = MFMA32(a0[k], kb0[4 * sb + k], st0); st1 = MFMA32(a1[k], kb0[4 * sb + k], st1); }
;         asm volatile("" : "+v"(st0), "+v"(st1) :: "memory");
; #pragma unroll
;         for (int k = 0; k < 4; ++k) kb0[4 * sb + k] = ldg16(kT, kboff0 + (unsigned)cn * 262144u + 1024u * (4 * sb + k));
;       }
; #pragma unroll
;       for (int t = 0; t < 2; ++t) {
;         const int sv = 2 * dq + t;
;         *(LAS bf16x8*)(vimg + ((cc + 1) & 1) * 16384 + et * 8192 + sv * 1024 + lane * 16) = scale_tab(vr[t], kdec + 16 * sv + 8 * h);
;         vr[t] = ldg16(vT, vaoff0 + (unsigned)cnn * 524288u + 1024u * sv);
;       }
;       LAS bf16_t* sw = Sb + (pbuf ^ 1) * SBE + (4 * h) * 264 + 32 * w + r;
; #pragma unroll
;       for (int i = 0; i < 16; ++i) {
;         const int eo = ((i & 3) + 8 * (i >> 2)) * 264;
;         const unsigned pkw = cvt_pk_bf16(st0[i], st1[i]);
;         sw[eo] = (bf16_t)(pkw & 0xffffu);
;         sw[eo + 32 * 264] = (bf16_t)(pkw >> 16);
;       }
;       lds_barrier();
;       pbuf ^= 1;
	v_mfma_f32_32x32x16_bf16 v[0:15], v[240:243], v[144:147], v[0:15]
	ds_read_b128 v[240:243], v169 offset:15360
	v_mov_b32_e32 v32, s8
	v_sub_u32_e64 v32, s5, v32 clamp
	v_lshl_add_u32 v61, v32, 19, v224
	s_and_b32 s8, s1, 0x4000
	v_add_u32_e32 v60, s8, v198
	v_add_u32_e32 v62, s3, v60
	v_or_b32_e32 v63, s3, v61
	s_waitcnt lgkmcnt(5)
	v_mfma_f32_32x32x16_bf16 v[16:31], v[244:247], v[136:139], v[16:31]
	v_or_b32_e32 v61, s33, v61
	s_mul_i32 s8, s0, 0x8400
	s_cmp_eq_u32 s4, s2
	s_waitcnt lgkmcnt(4)
	v_mfma_f32_32x32x16_bf16 v[0:15], v[248:251], v[136:139], v[0:15]
	s_waitcnt lgkmcnt(3)
	v_mfma_f32_32x32x16_bf16 v[16:31], v[228:231], v[132:135], v[16:31]
	s_waitcnt lgkmcnt(2)
	v_mfma_f32_32x32x16_bf16 v[0:15], v[232:235], v[132:135], v[0:15]
	v_add_u32_e32 v32, v184, v223
	v_or_b32_e32 v33, 0x400, v32
	v_or_b32_e32 v34, 0x800, v32
	v_or_b32_e32 v35, 0xc00, v32
	global_load_dwordx4 v[164:167], v32, s[14:15]
	global_load_dwordx4 v[160:163], v33, s[14:15]
	global_load_dwordx4 v[156:159], v34, s[14:15]
	global_load_dwordx4 v[140:143], v35, s[14:15]
	v_or_b32_e32 v132, 0x1000, v32
	s_waitcnt lgkmcnt(1)
	v_mfma_f32_32x32x16_bf16 v[16:31], v[236:239], v[128:131], v[16:31]
	v_or_b32_e32 v36, 0x1400, v32
	v_or_b32_e32 v37, 0x1800, v32
	v_or_b32_e32 v38, 0x1c00, v32
	s_waitcnt lgkmcnt(0)
	v_mfma_f32_32x32x16_bf16 v[0:15], v[240:243], v[128:131], v[0:15]
	ds_read_b128 v[32:35], v172
	global_load_dwordx4 v[144:147], v132, s[14:15]
	global_load_dwordx4 v[136:139], v36, s[14:15]
	s_nop 0
	global_load_dwordx4 v[132:135], v37, s[14:15]
	global_load_dwordx4 v[128:131], v38, s[14:15]
	ds_read_b128 v[36:39], v172 offset:16
	s_waitcnt lgkmcnt(1)
	v_mul_f32_e32 v32, v32, v46
	v_mul_f32_e32 v33, v33, v47
	v_mul_f32_e32 v34, v34, v48
	v_mul_f32_e32 v35, v35, v49
	s_waitcnt lgkmcnt(0)
	v_mul_f32_e32 v36, v36, v50
	v_mul_f32_e32 v37, v37, v51
	v_mul_f32_e32 v38, v38, v52
	v_mul_f32_e32 v39, v39, v53
	v_cvt_pk_bf16_f32 v32, v32, v33
	v_cvt_pk_bf16_f32 v33, v34, v35
	v_cvt_pk_bf16_f32 v34, v36, v37
	v_cvt_pk_bf16_f32 v35, v38, v39
	ds_write_b128 v62, v[32:35]
	global_load_dwordx4 v[152:155], v63, s[16:17]
	ds_read_b128 v[32:35], v173
	ds_read_b128 v[36:39], v173 offset:16
	s_waitcnt lgkmcnt(1)
	v_mul_f32_e32 v32, v32, v44
	v_mul_f32_e32 v33, v33, v45
	v_mul_f32_e32 v34, v34, v54
	v_mul_f32_e32 v35, v35, v55
	s_waitcnt lgkmcnt(0)
	v_mul_f32_e32 v36, v36, v56
	v_mul_f32_e32 v37, v37, v57
	v_mul_f32_e32 v38, v38, v58
	v_mul_f32_e32 v39, v39, v59
	v_cvt_pk_bf16_f32 v32, v32, v33
	v_cvt_pk_bf16_f32 v33, v34, v35
	v_cvt_pk_bf16_f32 v34, v36, v37
	v_cvt_pk_bf16_f32 v35, v38, v39
	global_load_dwordx4 v[148:151], v61, s[16:17]
	v_add_u32_e32 v37, s33, v60
	v_add_u32_e32 v36, s8, v199
	ds_write_b128 v37, v[32:35]
	v_mbcnt_lo_u32_b32 v251, -1, 0
	v_mbcnt_hi_u32_b32 v251, -1, v251
	v_and_b32_e32 v251, 1, v251
	v_sub_u32_e32 v250, 0, v251
	v_and_b32_e32 v248, 0x06060606, v250
	v_xor_b32_e32 v248, 0x05040100, v248
	v_and_b32_e32 v251, 0x107e, v250
	v_add_u32_e32 v249, v36, v251
	v_cvt_pk_bf16_f32 v232, v16, v20
	v_cvt_pk_bf16_f32 v233, v17, v21
	v_cvt_pk_bf16_f32 v234, v18, v22
	v_cvt_pk_bf16_f32 v235, v19, v23
	v_cvt_pk_bf16_f32 v236, v24, v28
	v_cvt_pk_bf16_f32 v237, v25, v29
	v_cvt_pk_bf16_f32 v238, v26, v30
	v_cvt_pk_bf16_f32 v239, v27, v31
	v_mov_b32_dpp v240, v232 quad_perm:[1,0,3,2] row_mask:0xf bank_mask:0xf
	v_mov_b32_dpp v241, v233 quad_perm:[1,0,3,2] row_mask:0xf bank_mask:0xf
	v_mov_b32_dpp v242, v234 quad_perm:[1,0,3,2] row_mask:0xf bank_mask:0xf
	v_mov_b32_dpp v243, v235 quad_perm:[1,0,3,2] row_mask:0xf bank_mask:0xf
	v_mov_b32_dpp v244, v236 quad_perm:[1,0,3,2] row_mask:0xf bank_mask:0xf
	v_mov_b32_dpp v245, v237 quad_perm:[1,0,3,2] row_mask:0xf bank_mask:0xf
	v_mov_b32_dpp v246, v238 quad_perm:[1,0,3,2] row_mask:0xf bank_mask:0xf
	v_mov_b32_dpp v247, v239 quad_perm:[1,0,3,2] row_mask:0xf bank_mask:0xf
	v_perm_b32 v240, v240, v232, v248
	v_perm_b32 v241, v241, v233, v248
	v_perm_b32 v242, v242, v234, v248
	v_perm_b32 v243, v243, v235, v248
	v_perm_b32 v244, v244, v236, v248
	v_perm_b32 v245, v245, v237, v248
	v_perm_b32 v246, v246, v238, v248
	v_perm_b32 v247, v247, v239, v248
	ds_write_b32 v249, v240 offset:0
	ds_write_b32 v249, v241 offset:528
	ds_write_b32 v249, v242 offset:1056
	ds_write_b32 v249, v243 offset:1584
	ds_write_b32 v249, v244 offset:8448
	ds_write_b32 v249, v245 offset:8976
	ds_write_b32 v249, v246 offset:9504
	ds_write_b32 v249, v247 offset:10032
	v_cvt_pk_bf16_f32 v232, v0, v4
	v_cvt_pk_bf16_f32 v233, v1, v5
	v_cvt_pk_bf16_f32 v234, v2, v6
	v_cvt_pk_bf16_f32 v235, v3, v7
	v_cvt_pk_bf16_f32 v236, v8, v12
	v_cvt_pk_bf16_f32 v237, v9, v13
	v_cvt_pk_bf16_f32 v238, v10, v14
	v_cvt_pk_bf16_f32 v239, v11, v15
	v_mov_b32_dpp v240, v232 quad_perm:[1,0,3,2] row_mask:0xf bank_mask:0xf
	v_mov_b32_dpp v241, v233 quad_perm:[1,0,3,2] row_mask:0xf bank_mask:0xf
	v_mov_b32_dpp v242, v234 quad_perm:[1,0,3,2] row_mask:0xf bank_mask:0xf
	v_mov_b32_dpp v243, v235 quad_perm:[1,0,3,2] row_mask:0xf bank_mask:0xf
	v_mov_b32_dpp v244, v236 quad_perm:[1,0,3,2] row_mask:0xf bank_mask:0xf
	v_mov_b32_dpp v245, v237 quad_perm:[1,0,3,2] row_mask:0xf bank_mask:0xf
	v_mov_b32_dpp v246, v238 quad_perm:[1,0,3,2] row_mask:0xf bank_mask:0xf
	v_mov_b32_dpp v247, v239 quad_perm:[1,0,3,2] row_mask:0xf bank_mask:0xf
	v_perm_b32 v240, v240, v232, v248
	v_perm_b32 v241, v241, v233, v248
	v_perm_b32 v242, v242, v234, v248
	v_perm_b32 v243, v243, v235, v248
	v_perm_b32 v244, v244, v236, v248
	v_perm_b32 v245, v245, v237, v248
	v_perm_b32 v246, v246, v238, v248
	v_perm_b32 v247, v247, v239, v248
	ds_write_b32 v249, v240 offset:16896
	ds_write_b32 v249, v241 offset:17424
	ds_write_b32 v249, v242 offset:17952
	ds_write_b32 v249, v243 offset:18480
	ds_write_b32 v249, v244 offset:25344
	ds_write_b32 v249, v245 offset:25872
	ds_write_b32 v249, v246 offset:26400
	ds_write_b32 v249, v247 offset:26928
	s_waitcnt lgkmcnt(0)
	s_barrier
	s_mov_b32 s8, s2
	s_cbranch_scc0 .LBB0_108
	s_branch .LBB0_68
